# K-loop priority inverted: s_setprio 1 during each load segment (ds_read + LDS-DMA issue) and 0 during the MFMA block, so the loading wave is not starved behind its partner's MFMAs
# baseline (speedup 1.0000x reference)
; #define PG8_STAGE(bufoff, gbase, voff) do { _Pragma("unroll") for (int _i = 0; _i < 2; ++_i) \
;         __builtin_amdgcn_global_load_lds((const unsigned*)((const char*)(gbase) + (voff)[_i]), (PG8_LAS unsigned*)(lds + (bufoff) + ldsw + _i * 8192), 16, 0, 0); } while (0)
; #define PG8_LDA(dst, b, h) do { _Pragma("unroll") for (int m = 0; m < 4; ++m) _Pragma("unroll") for (int k = 0; k < 2; ++k) dst[m][k] = *(const PG8_LAS bf16x8*)(lds + PG8_SA(b, h) + aoff + m * 2048 + k * 1024); } while (0)
; #define PG8_LDB(dst, b, h) do { _Pragma("unroll") for (int n = 0; n < 2; ++n) _Pragma("unroll") for (int k = 0; k < 2; ++k) dst[n][k] = *(const PG8_LAS bf16x8*)(lds + PG8_SB(b, h) + boff + n * 2048 + k * 1024); } while (0)
; #define PG8_MMA(ai, bj, At, Bt) do { __builtin_amdgcn_s_setprio(1); _Pragma("unroll") for (int m = 0; m < 4; ++m) _Pragma("unroll") for (int n = 0; n < 2; ++n) _Pragma("unroll") for (int k = 0; k < 2; ++k) \
;         acc[ai][bj][m][n] = __builtin_amdgcn_mfma_f32_16x16x32_bf16(Bt[n][k], At[m][k], acc[ai][bj][m][n], 0, 0, 0); __builtin_amdgcn_s_setprio(0); } while (0)
; #define PG8_WAIT_V(n) asm volatile("s_waitcnt vmcnt(" #n ")" ::: "memory")
; #define PG8_WAIT_L(n) asm volatile("s_waitcnt lgkmcnt(" #n ")" ::: "memory")
; #define PG8_BAR __builtin_amdgcn_s_barrier()
; template <class Epi, class Sched, bool ALIGN_EPI = false, bool SP2 = false>
; __device__ __forceinline__ void gemm_phase(PG8_LAS unsigned char* lds, const Gemm g, const Sched& S, const Epi& E) {
;     ...
;             const char* a1 = cA + (size_t)(t + 1) * kstep;
;             const char* a2 = last ? nA : cA + (size_t)(t + 2) * kstep; const char* b2 = last ? nB : cB + (size_t)(t + 2) * kstep;
;             const char* a3 = a2 + kstep; const char* b3 = b2 + kstep;
;             if (last && has_next) S.a_ready(nxt);
;             if constexpr (SP2) {
;             PG8_LDB(B0, 0, 0); PG8_LDB(B1, 0, 1); PG8_SCHED; PG8_LDA(At, 0, 0); PG8_STAGE(PG8_SA(1, 1), a1 + hstepA, voffA);
;             PG8_WAIT_V(8); PG8_WAIT_L(0); PG8_BAR; PG8_MMA(0, 0, At, B0); PG8_MMA(0, 1, At, B1); PG8_BAR; PG8_SCHED;
;             PG8_LDA(At, 0, 1); PG8_STAGE(PG8_SB(0, 0), b2, voffB); PG8_STAGE(PG8_SB(0, 1), b2 + hstepB, voffB); PG8_STAGE(PG8_SA(0, 0), a2, voffA);
;             PG8_WAIT_V(8); PG8_WAIT_L(0); PG8_BAR; PG8_MMA(1, 0, At, B0); PG8_MMA(1, 1, At, B1); PG8_BAR; PG8_SCHED;
.LBB0_634:
	s_add_u32 s2, s0, 0xfffc0080
	s_addc_u32 s3, s1, -1
	s_add_i32 s30, 0, 0x10000
	s_cmp_eq_u32 s95, 12
	s_cselect_b32 s85, s17, s3
	s_cselect_b32 s84, s78, s2
	s_cselect_b32 s7, s15, s94
	s_cselect_b32 s6, s87, s93
	s_add_i32 s31, 0, 0x14000
	v_add_u32_e32 v140, s30, v230
	v_add_u32_e32 v156, s31, v230
	ds_read_b128 v[112:115], v140
	ds_read_b128 v[120:123], v140 offset:1024
	ds_read_b128 v[128:131], v140 offset:2048
	ds_read_b128 v[140:143], v140 offset:3072
	ds_read_b128 v[144:147], v156
	ds_read_b128 v[148:151], v156 offset:1024
	ds_read_b128 v[152:155], v156 offset:2048
	ds_read_b128 v[156:159], v156 offset:3072
	s_add_i32 m0, s20, 0xc000
	ds_read_b128 v[160:163], v231
	ds_read_b128 v[164:167], v231 offset:1024
	ds_read_b128 v[168:171], v231 offset:2048
	ds_read_b128 v[172:175], v231 offset:3072
	ds_read_b128 v[186:189], v231 offset:4096
	ds_read_b128 v[198:201], v231 offset:5120
	ds_read_b128 v[202:205], v231 offset:6144
	ds_read_b128 v[206:209], v231 offset:7168
	global_load_lds_dwordx4 v184, s[0:1]
	s_add_i32 m0, s20, 0xe000
	s_nop 0
	global_load_lds_dwordx4 v182, s[0:1]
	s_waitcnt vmcnt(8)
	s_waitcnt lgkmcnt(0)
	s_barrier
	s_setprio 0
	s_waitcnt lgkmcnt(0)
	v_mfma_f32_16x16x32_bf16 v[136:139], v[112:115], v[160:163], v[136:139]
	v_mfma_f32_16x16x32_bf16 v[132:135], v[128:131], v[160:163], v[132:135]
	v_mfma_f32_16x16x32_bf16 v[108:111], v[112:115], v[168:171], v[108:111]
	v_mfma_f32_16x16x32_bf16 v[104:107], v[128:131], v[168:171], v[104:107]
	v_mfma_f32_16x16x32_bf16 v[92:95], v[112:115], v[186:189], v[92:95]
	v_mfma_f32_16x16x32_bf16 v[88:91], v[128:131], v[186:189], v[88:91]
	v_mfma_f32_16x16x32_bf16 v[76:79], v[112:115], v[202:205], v[76:79]
	v_mfma_f32_16x16x32_bf16 v[72:75], v[128:131], v[202:205], v[72:75]
	v_mfma_f32_16x16x32_bf16 v[136:139], v[120:123], v[164:167], v[136:139]
	v_mfma_f32_16x16x32_bf16 v[132:135], v[140:143], v[164:167], v[132:135]
	v_mfma_f32_16x16x32_bf16 v[108:111], v[120:123], v[172:175], v[108:111]
	v_mfma_f32_16x16x32_bf16 v[104:107], v[140:143], v[172:175], v[104:107]
	v_mfma_f32_16x16x32_bf16 v[92:95], v[120:123], v[198:201], v[92:95]
	v_mfma_f32_16x16x32_bf16 v[88:91], v[140:143], v[198:201], v[88:91]
	v_mfma_f32_16x16x32_bf16 v[76:79], v[120:123], v[206:209], v[76:79]
	v_mfma_f32_16x16x32_bf16 v[72:75], v[140:143], v[206:209], v[72:75]
	v_mfma_f32_16x16x32_bf16 v[124:127], v[144:147], v[160:163], v[124:127]
	v_mfma_f32_16x16x32_bf16 v[116:119], v[152:155], v[160:163], v[116:119]
	v_mfma_f32_16x16x32_bf16 v[100:103], v[144:147], v[168:171], v[100:103]
	v_mfma_f32_16x16x32_bf16 v[96:99], v[152:155], v[168:171], v[96:99]
	v_mfma_f32_16x16x32_bf16 v[84:87], v[144:147], v[186:189], v[84:87]
	v_mfma_f32_16x16x32_bf16 v[80:83], v[152:155], v[186:189], v[80:83]
	v_mfma_f32_16x16x32_bf16 v[68:71], v[144:147], v[202:205], v[68:71]
	v_mfma_f32_16x16x32_bf16 v[64:67], v[152:155], v[202:205], v[64:67]
	v_mfma_f32_16x16x32_bf16 v[124:127], v[148:151], v[164:167], v[124:127]
	v_mfma_f32_16x16x32_bf16 v[116:119], v[156:159], v[164:167], v[116:119]
	v_mfma_f32_16x16x32_bf16 v[100:103], v[148:151], v[172:175], v[100:103]
	v_mfma_f32_16x16x32_bf16 v[96:99], v[156:159], v[172:175], v[96:99]
	v_mfma_f32_16x16x32_bf16 v[84:87], v[148:151], v[198:201], v[84:87]
	v_mfma_f32_16x16x32_bf16 v[80:83], v[156:159], v[198:201], v[80:83]
	v_mfma_f32_16x16x32_bf16 v[68:71], v[148:151], v[206:209], v[68:71]
	v_mfma_f32_16x16x32_bf16 v[64:67], v[156:159], v[206:209], v[64:67]
	s_barrier
	s_setprio 1
	s_add_i32 s2, s30, s19
	s_mov_b32 m0, s2
	ds_read_b128 v[160:163], v231 offset:16384
	ds_read_b128 v[164:167], v231 offset:17408
	ds_read_b128 v[168:171], v231 offset:18432
	ds_read_b128 v[172:175], v231 offset:19456
	ds_read_b128 v[186:189], v231 offset:20480
	ds_read_b128 v[198:201], v231 offset:21504
	ds_read_b128 v[202:205], v231 offset:22528
	ds_read_b128 v[206:209], v231 offset:23552
	global_load_lds_dwordx4 v192, s[6:7]
	s_add_i32 m0, s2, 0x2000
	s_add_u32 s2, s6, 0x40000
	s_addc_u32 s3, s7, 0
	s_add_i32 s30, s31, s19
	global_load_lds_dwordx4 v176, s[6:7]
	s_mov_b32 m0, s30
	s_nop 0
	global_load_lds_dwordx4 v192, s[2:3]
	s_add_i32 m0, s30, 0x2000
	s_nop 0
	global_load_lds_dwordx4 v176, s[2:3]
	s_mov_b32 m0, s20
	s_nop 0
	global_load_lds_dwordx4 v180, s[84:85]
	s_mov_b32 m0, s21
	s_nop 0
	global_load_lds_dwordx4 v178, s[84:85]
	s_waitcnt vmcnt(8)
	s_waitcnt lgkmcnt(0)
	s_barrier
	s_setprio 0
	s_waitcnt lgkmcnt(0)
	v_mfma_f32_16x16x32_bf16 v[60:63], v[112:115], v[160:163], v[60:63]
	v_mfma_f32_16x16x32_bf16 v[56:59], v[128:131], v[160:163], v[56:59]
	v_mfma_f32_16x16x32_bf16 v[44:47], v[112:115], v[168:171], v[44:47]
	v_mfma_f32_16x16x32_bf16 v[40:43], v[128:131], v[168:171], v[40:43]
	v_mfma_f32_16x16x32_bf16 v[28:31], v[112:115], v[186:189], v[28:31]
	v_mfma_f32_16x16x32_bf16 v[24:27], v[128:131], v[186:189], v[24:27]
	v_mfma_f32_16x16x32_bf16 v[12:15], v[112:115], v[202:205], v[12:15]
	v_mfma_f32_16x16x32_bf16 v[8:11], v[128:131], v[202:205], v[8:11]
	v_mfma_f32_16x16x32_bf16 v[60:63], v[120:123], v[164:167], v[60:63]
	v_mfma_f32_16x16x32_bf16 v[56:59], v[140:143], v[164:167], v[56:59]
	v_mfma_f32_16x16x32_bf16 v[44:47], v[120:123], v[172:175], v[44:47]
	v_mfma_f32_16x16x32_bf16 v[40:43], v[140:143], v[172:175], v[40:43]
	v_mfma_f32_16x16x32_bf16 v[28:31], v[120:123], v[198:201], v[28:31]
	v_mfma_f32_16x16x32_bf16 v[24:27], v[140:143], v[198:201], v[24:27]
	v_mfma_f32_16x16x32_bf16 v[12:15], v[120:123], v[206:209], v[12:15]
	v_mfma_f32_16x16x32_bf16 v[8:11], v[140:143], v[206:209], v[8:11]
	v_mfma_f32_16x16x32_bf16 v[52:55], v[144:147], v[160:163], v[52:55]
	v_mfma_f32_16x16x32_bf16 v[48:51], v[152:155], v[160:163], v[48:51]
	v_mfma_f32_16x16x32_bf16 v[36:39], v[144:147], v[168:171], v[36:39]
	v_mfma_f32_16x16x32_bf16 v[32:35], v[152:155], v[168:171], v[32:35]
	v_mfma_f32_16x16x32_bf16 v[20:23], v[144:147], v[186:189], v[20:23]
	v_mfma_f32_16x16x32_bf16 v[16:19], v[152:155], v[186:189], v[16:19]
	v_mfma_f32_16x16x32_bf16 v[4:7], v[144:147], v[202:205], v[4:7]
	v_mfma_f32_16x16x32_bf16 v[0:3], v[152:155], v[202:205], v[0:3]
	v_mfma_f32_16x16x32_bf16 v[52:55], v[148:151], v[164:167], v[52:55]
	v_mfma_f32_16x16x32_bf16 v[48:51], v[156:159], v[164:167], v[48:51]
	v_mfma_f32_16x16x32_bf16 v[36:39], v[148:151], v[172:175], v[36:39]
	v_mfma_f32_16x16x32_bf16 v[32:35], v[156:159], v[172:175], v[32:35]
	v_mfma_f32_16x16x32_bf16 v[20:23], v[148:151], v[198:201], v[20:23]
	v_mfma_f32_16x16x32_bf16 v[16:19], v[156:159], v[198:201], v[16:19]
	v_mfma_f32_16x16x32_bf16 v[4:7], v[148:151], v[206:209], v[4:7]
	v_mfma_f32_16x16x32_bf16 v[0:3], v[156:159], v[206:209], v[0:3]
	s_barrier
; #define PG8_STAGE(bufoff, gbase, voff) do { _Pragma("unroll") for (int _i = 0; _i < 2; ++_i) \
;         __builtin_amdgcn_global_load_lds((const unsigned*)((const char*)(gbase) + (voff)[_i]), (PG8_LAS unsigned*)(lds + (bufoff) + ldsw + _i * 8192), 16, 0, 0); } while (0)
; #define PG8_LDA(dst, b, h) do { _Pragma("unroll") for (int m = 0; m < 4; ++m) _Pragma("unroll") for (int k = 0; k < 2; ++k) dst[m][k] = *(const PG8_LAS bf16x8*)(lds + PG8_SA(b, h) + aoff + m * 2048 + k * 1024); } while (0)
; #define PG8_LDB(dst, b, h) do { _Pragma("unroll") for (int n = 0; n < 2; ++n) _Pragma("unroll") for (int k = 0; k < 2; ++k) dst[n][k] = *(const PG8_LAS bf16x8*)(lds + PG8_SB(b, h) + boff + n * 2048 + k * 1024); } while (0)
; #define PG8_MMA(ai, bj, At, Bt) do { __builtin_amdgcn_s_setprio(1); _Pragma("unroll") for (int m = 0; m < 4; ++m) _Pragma("unroll") for (int n = 0; n < 2; ++n) _Pragma("unroll") for (int k = 0; k < 2; ++k) \
;         acc[ai][bj][m][n] = __builtin_amdgcn_mfma_f32_16x16x32_bf16(Bt[n][k], At[m][k], acc[ai][bj][m][n], 0, 0, 0); __builtin_amdgcn_s_setprio(0); } while (0)
; #define PG8_WAIT_V(n) asm volatile("s_waitcnt vmcnt(" #n ")" ::: "memory")
; #define PG8_WAIT_L(n) asm volatile("s_waitcnt lgkmcnt(" #n ")" ::: "memory")
; #define PG8_BAR __builtin_amdgcn_s_barrier()
; #define PG8_SCHED __builtin_amdgcn_sched_barrier(0)
; template <class Epi, class Sched, bool ALIGN_EPI = false, bool SP2 = false>
; __device__ __forceinline__ void gemm_phase(PG8_LAS unsigned char* lds, const Gemm g, const Sched& S, const Epi& E) {
;     ...
;             PG8_LDB(B0, 1, 0); PG8_LDB(B1, 1, 1); PG8_SCHED; PG8_LDA(At, 1, 0); PG8_STAGE(PG8_SA(0, 1), a2 + hstepA, voffA);
;             PG8_WAIT_V(8); PG8_WAIT_L(0); PG8_BAR; PG8_MMA(0, 0, At, B0); PG8_MMA(0, 1, At, B1); PG8_BAR; PG8_SCHED;
;             PG8_LDA(At, 1, 1); PG8_STAGE(PG8_SB(1, 0), b3, voffB); PG8_STAGE(PG8_SB(1, 1), b3 + hstepB, voffB); PG8_STAGE(PG8_SA(1, 0), a3, voffA);
;             PG8_WAIT_V(8); PG8_WAIT_L(0); PG8_BAR; PG8_MMA(1, 0, At, B0); PG8_MMA(1, 1, At, B1); PG8_BAR; PG8_SCHED;
	s_setprio 1
	s_add_i32 s30, 0, 0x18000
	s_add_i32 s31, 0, 0x1c000
	v_add_u32_e32 v140, s30, v230
	v_add_u32_e32 v156, s31, v230
	ds_read_b128 v[112:115], v140
	ds_read_b128 v[120:123], v140 offset:1024
	ds_read_b128 v[128:131], v140 offset:2048
	ds_read_b128 v[140:143], v140 offset:3072
	ds_read_b128 v[144:147], v156
	ds_read_b128 v[148:151], v156 offset:1024
	ds_read_b128 v[152:155], v156 offset:2048
	ds_read_b128 v[156:159], v156 offset:3072
	s_add_u32 s2, s84, 0x40000
	s_addc_u32 s3, s85, 0
	s_mov_b32 m0, s45
	ds_read_b128 v[160:163], v231 offset:32768
	ds_read_b128 v[164:167], v231 offset:33792
	ds_read_b128 v[168:171], v231 offset:34816
	ds_read_b128 v[172:175], v231 offset:35840
	ds_read_b128 v[186:189], v231 offset:36864
	ds_read_b128 v[198:201], v231 offset:37888
	ds_read_b128 v[202:205], v231 offset:38912
	ds_read_b128 v[206:209], v231 offset:39936
	global_load_lds_dwordx4 v180, s[2:3]
	s_mov_b32 m0, s49
	s_nop 0
	global_load_lds_dwordx4 v178, s[2:3]
	s_waitcnt vmcnt(8)
	s_waitcnt lgkmcnt(0)
	s_barrier
	s_setprio 0
	s_waitcnt lgkmcnt(0)
	v_mfma_f32_16x16x32_bf16 v[136:139], v[112:115], v[160:163], v[136:139]
	v_mfma_f32_16x16x32_bf16 v[132:135], v[128:131], v[160:163], v[132:135]
	v_mfma_f32_16x16x32_bf16 v[108:111], v[112:115], v[168:171], v[108:111]
	v_mfma_f32_16x16x32_bf16 v[104:107], v[128:131], v[168:171], v[104:107]
	v_mfma_f32_16x16x32_bf16 v[92:95], v[112:115], v[186:189], v[92:95]
	v_mfma_f32_16x16x32_bf16 v[88:91], v[128:131], v[186:189], v[88:91]
	v_mfma_f32_16x16x32_bf16 v[76:79], v[112:115], v[202:205], v[76:79]
	v_mfma_f32_16x16x32_bf16 v[72:75], v[128:131], v[202:205], v[72:75]
	v_mfma_f32_16x16x32_bf16 v[136:139], v[120:123], v[164:167], v[136:139]
	v_mfma_f32_16x16x32_bf16 v[132:135], v[140:143], v[164:167], v[132:135]
	v_mfma_f32_16x16x32_bf16 v[108:111], v[120:123], v[172:175], v[108:111]
	v_mfma_f32_16x16x32_bf16 v[104:107], v[140:143], v[172:175], v[104:107]
	v_mfma_f32_16x16x32_bf16 v[92:95], v[120:123], v[198:201], v[92:95]
	v_mfma_f32_16x16x32_bf16 v[88:91], v[140:143], v[198:201], v[88:91]
	v_mfma_f32_16x16x32_bf16 v[76:79], v[120:123], v[206:209], v[76:79]
	v_mfma_f32_16x16x32_bf16 v[72:75], v[140:143], v[206:209], v[72:75]
	v_mfma_f32_16x16x32_bf16 v[124:127], v[144:147], v[160:163], v[124:127]
	v_mfma_f32_16x16x32_bf16 v[116:119], v[152:155], v[160:163], v[116:119]
	v_mfma_f32_16x16x32_bf16 v[100:103], v[144:147], v[168:171], v[100:103]
	v_mfma_f32_16x16x32_bf16 v[96:99], v[152:155], v[168:171], v[96:99]
	v_mfma_f32_16x16x32_bf16 v[84:87], v[144:147], v[186:189], v[84:87]
	v_mfma_f32_16x16x32_bf16 v[80:83], v[152:155], v[186:189], v[80:83]
	v_mfma_f32_16x16x32_bf16 v[68:71], v[144:147], v[202:205], v[68:71]
	v_mfma_f32_16x16x32_bf16 v[64:67], v[152:155], v[202:205], v[64:67]
	v_mfma_f32_16x16x32_bf16 v[124:127], v[148:151], v[164:167], v[124:127]
	v_mfma_f32_16x16x32_bf16 v[116:119], v[156:159], v[164:167], v[116:119]
	v_mfma_f32_16x16x32_bf16 v[100:103], v[148:151], v[172:175], v[100:103]
	v_mfma_f32_16x16x32_bf16 v[96:99], v[156:159], v[172:175], v[96:99]
	v_mfma_f32_16x16x32_bf16 v[84:87], v[148:151], v[198:201], v[84:87]
	v_mfma_f32_16x16x32_bf16 v[80:83], v[156:159], v[198:201], v[80:83]
	v_mfma_f32_16x16x32_bf16 v[68:71], v[148:151], v[206:209], v[68:71]
	v_mfma_f32_16x16x32_bf16 v[64:67], v[156:159], v[206:209], v[64:67]
	s_barrier
	s_setprio 1
	s_add_i32 s2, s30, s19
	s_add_i32 m0, s2, 0xffffff80
	ds_read_b128 v[160:163], v231 offset:49152
	ds_read_b128 v[164:167], v231 offset:50176
	ds_read_b128 v[168:171], v231 offset:51200
	ds_read_b128 v[172:175], v231 offset:52224
	ds_read_b128 v[186:189], v231 offset:53248
	ds_read_b128 v[198:201], v231 offset:54272
	ds_read_b128 v[202:205], v231 offset:55296
	ds_read_b128 v[206:209], v231 offset:56320
	global_load_lds_dwordx4 v192, s[6:7] offset:128
	s_add_i32 m0, s2, 0x1f80
	s_add_u32 s2, s6, 0x40080
	global_load_lds_dwordx4 v176, s[6:7] offset:128
	s_addc_u32 s3, s7, 0
	s_add_i32 s6, s31, s19
	s_mov_b32 m0, s6
	s_nop 0
	global_load_lds_dwordx4 v192, s[2:3]
	s_add_i32 m0, s6, 0x2000
	s_nop 0
	global_load_lds_dwordx4 v176, s[2:3]
	s_add_i32 m0, s65, 0xffffff80
	s_nop 0
	global_load_lds_dwordx4 v180, s[84:85] offset:128
	s_add_i32 m0, s80, 0xffffff80
	s_nop 0
	global_load_lds_dwordx4 v178, s[84:85] offset:128
	s_waitcnt vmcnt(8)
	s_waitcnt lgkmcnt(0)
	s_barrier
	s_setprio 0
	s_waitcnt lgkmcnt(0)
	v_mfma_f32_16x16x32_bf16 v[60:63], v[112:115], v[160:163], v[60:63]
	v_mfma_f32_16x16x32_bf16 v[56:59], v[128:131], v[160:163], v[56:59]
	v_mfma_f32_16x16x32_bf16 v[44:47], v[112:115], v[168:171], v[44:47]
	v_mfma_f32_16x16x32_bf16 v[40:43], v[128:131], v[168:171], v[40:43]
	v_mfma_f32_16x16x32_bf16 v[28:31], v[112:115], v[186:189], v[28:31]
	v_mfma_f32_16x16x32_bf16 v[24:27], v[128:131], v[186:189], v[24:27]
	v_mfma_f32_16x16x32_bf16 v[12:15], v[112:115], v[202:205], v[12:15]
	v_mfma_f32_16x16x32_bf16 v[8:11], v[128:131], v[202:205], v[8:11]
	v_mfma_f32_16x16x32_bf16 v[60:63], v[120:123], v[164:167], v[60:63]
	v_mfma_f32_16x16x32_bf16 v[56:59], v[140:143], v[164:167], v[56:59]
	v_mfma_f32_16x16x32_bf16 v[44:47], v[120:123], v[172:175], v[44:47]
	v_mfma_f32_16x16x32_bf16 v[40:43], v[140:143], v[172:175], v[40:43]
	v_mfma_f32_16x16x32_bf16 v[28:31], v[120:123], v[198:201], v[28:31]
	v_mfma_f32_16x16x32_bf16 v[24:27], v[140:143], v[198:201], v[24:27]
	v_mfma_f32_16x16x32_bf16 v[12:15], v[120:123], v[206:209], v[12:15]
	v_mfma_f32_16x16x32_bf16 v[8:11], v[140:143], v[206:209], v[8:11]
	v_mfma_f32_16x16x32_bf16 v[52:55], v[144:147], v[160:163], v[52:55]
	v_mfma_f32_16x16x32_bf16 v[48:51], v[152:155], v[160:163], v[48:51]
	v_mfma_f32_16x16x32_bf16 v[36:39], v[144:147], v[168:171], v[36:39]
	v_mfma_f32_16x16x32_bf16 v[32:35], v[152:155], v[168:171], v[32:35]
	v_mfma_f32_16x16x32_bf16 v[20:23], v[144:147], v[186:189], v[20:23]
	v_mfma_f32_16x16x32_bf16 v[16:19], v[152:155], v[186:189], v[16:19]
	v_mfma_f32_16x16x32_bf16 v[4:7], v[144:147], v[202:205], v[4:7]
	v_mfma_f32_16x16x32_bf16 v[0:3], v[152:155], v[202:205], v[0:3]
	v_mfma_f32_16x16x32_bf16 v[52:55], v[148:151], v[164:167], v[52:55]
	v_mfma_f32_16x16x32_bf16 v[48:51], v[156:159], v[164:167], v[48:51]
	v_mfma_f32_16x16x32_bf16 v[36:39], v[148:151], v[172:175], v[36:39]
	v_mfma_f32_16x16x32_bf16 v[32:35], v[156:159], v[172:175], v[32:35]
	v_mfma_f32_16x16x32_bf16 v[20:23], v[148:151], v[198:201], v[20:23]
	v_mfma_f32_16x16x32_bf16 v[16:19], v[156:159], v[198:201], v[16:19]
	v_mfma_f32_16x16x32_bf16 v[4:7], v[148:151], v[206:209], v[4:7]
	v_mfma_f32_16x16x32_bf16 v[0:3], v[156:159], v[206:209], v[0:3]
	s_barrier
	s_setprio 1
	s_add_i32 s95, s95, 2
	s_add_u32 s93, s93, 0x100
	s_addc_u32 s94, s94, 0
	s_add_u32 s0, s0, 0x100
	s_addc_u32 s1, s1, 0
	s_cmp_gt_u32 s95, 13
	s_cbranch_scc0 .LBB0_634
	s_and_b64 vcc, exec, s[12:13]
	s_cbranch_vccz .LBB0_637
	s_barrier

; #define PG8_STAGE(bufoff, gbase, voff) do { _Pragma("unroll") for (int _i = 0; _i < 2; ++_i) \
;         __builtin_amdgcn_global_load_lds((const unsigned*)((const char*)(gbase) + (voff)[_i]), (PG8_LAS unsigned*)(lds + (bufoff) + ldsw + _i * 8192), 16, 0, 0); } while (0)
; #define PG8_LDA(dst, b, h) do { _Pragma("unroll") for (int m = 0; m < 4; ++m) _Pragma("unroll") for (int k = 0; k < 2; ++k) dst[m][k] = *(const PG8_LAS bf16x8*)(lds + PG8_SA(b, h) + aoff + m * 2048 + k * 1024); } while (0)
; #define PG8_LDB(dst, b, h) do { _Pragma("unroll") for (int n = 0; n < 2; ++n) _Pragma("unroll") for (int k = 0; k < 2; ++k) dst[n][k] = *(const PG8_LAS bf16x8*)(lds + PG8_SB(b, h) + boff + n * 2048 + k * 1024); } while (0)
; #define PG8_MMA(ai, bj, At, Bt) do { __builtin_amdgcn_s_setprio(1); _Pragma("unroll") for (int m = 0; m < 4; ++m) _Pragma("unroll") for (int n = 0; n < 2; ++n) _Pragma("unroll") for (int k = 0; k < 2; ++k) \
;         acc[ai][bj][m][n] = __builtin_amdgcn_mfma_f32_16x16x32_bf16(Bt[n][k], At[m][k], acc[ai][bj][m][n], 0, 0, 0); __builtin_amdgcn_s_setprio(0); } while (0)
; #define PG8_WAIT_V(n) asm volatile("s_waitcnt vmcnt(" #n ")" ::: "memory")
; #define PG8_WAIT_L(n) asm volatile("s_waitcnt lgkmcnt(" #n ")" ::: "memory")
; #define PG8_BAR __builtin_amdgcn_s_barrier()
; template <class Epi, class Sched, bool ALIGN_EPI = false, bool SP2 = false>
; __device__ __forceinline__ void gemm_phase(PG8_LAS unsigned char* lds, const Gemm g, const Sched& S, const Epi& E) {
;     ...
;             const char* a1 = cA + (size_t)(t + 1) * kstep;
;             const char* a2 = last ? nA : cA + (size_t)(t + 2) * kstep; const char* b2 = last ? nB : cB + (size_t)(t + 2) * kstep;
;             const char* a3 = a2 + kstep; const char* b3 = b2 + kstep;
;             if (last && has_next) S.a_ready(nxt);
;             if constexpr (SP2) {
;             PG8_LDB(B0, 0, 0); PG8_LDB(B1, 0, 1); PG8_SCHED; PG8_LDA(At, 0, 0); PG8_STAGE(PG8_SA(1, 1), a1 + hstepA, voffA);
;             PG8_WAIT_V(8); PG8_WAIT_L(0); PG8_BAR; PG8_MMA(0, 0, At, B0); PG8_MMA(0, 1, At, B1); PG8_BAR; PG8_SCHED;
;             PG8_LDA(At, 0, 1); PG8_STAGE(PG8_SB(0, 0), b2, voffB); PG8_STAGE(PG8_SB(0, 1), b2 + hstepB, voffB); PG8_STAGE(PG8_SA(0, 0), a2, voffA);
;             PG8_WAIT_V(8); PG8_WAIT_L(0); PG8_BAR; PG8_MMA(1, 0, At, B0); PG8_MMA(1, 1, At, B1); PG8_BAR; PG8_SCHED;
.LBB0_693:
	s_add_u32 s2, s4, 0xfffc0080
	s_addc_u32 s3, s5, -1
	s_add_i32 s30, 0, 0x10000
	s_cmp_eq_u32 s92, 12
	s_cselect_b32 s87, s17, s3
	s_cselect_b32 s86, s78, s2
	s_cselect_b32 s85, s15, s91
	s_cselect_b32 s84, s89, s90
	s_add_i32 s31, 0, 0x14000
	v_add_u32_e32 v140, s30, v182
	v_add_u32_e32 v166, s31, v182
	ds_read_b128 v[128:131], v140
	ds_read_b128 v[132:135], v140 offset:1024
	ds_read_b128 v[136:139], v140 offset:2048
	ds_read_b128 v[140:143], v140 offset:3072
	ds_read_b128 v[144:147], v166
	ds_read_b128 v[148:151], v166 offset:1024
	ds_read_b128 v[152:155], v166 offset:2048
	ds_read_b128 v[166:169], v166 offset:3072
	s_add_i32 m0, s20, 0xc000
	ds_read_b128 v[170:173], v183
	ds_read_b128 v[174:177], v183 offset:1024
	ds_read_b128 v[178:181], v183 offset:2048
	ds_read_b128 v[184:187], v183 offset:3072
	ds_read_b128 v[188:191], v183 offset:4096
	ds_read_b128 v[198:201], v183 offset:5120
	ds_read_b128 v[202:205], v183 offset:6144
	ds_read_b128 v[206:209], v183 offset:7168
	global_load_lds_dwordx4 v164, s[4:5]
	s_add_i32 m0, s20, 0xe000
	s_nop 0
	global_load_lds_dwordx4 v162, s[4:5]
	s_waitcnt vmcnt(8)
	s_waitcnt lgkmcnt(0)
	s_barrier
	s_setprio 0
	s_waitcnt lgkmcnt(0)
	v_mfma_f32_16x16x32_bf16 v[124:127], v[128:131], v[170:173], v[124:127]
	v_mfma_f32_16x16x32_bf16 v[120:123], v[136:139], v[170:173], v[120:123]
	v_mfma_f32_16x16x32_bf16 v[108:111], v[128:131], v[178:181], v[108:111]
	v_mfma_f32_16x16x32_bf16 v[104:107], v[136:139], v[178:181], v[104:107]
	v_mfma_f32_16x16x32_bf16 v[92:95], v[128:131], v[188:191], v[92:95]
	v_mfma_f32_16x16x32_bf16 v[88:91], v[136:139], v[188:191], v[88:91]
	v_mfma_f32_16x16x32_bf16 v[76:79], v[128:131], v[202:205], v[76:79]
	v_mfma_f32_16x16x32_bf16 v[72:75], v[136:139], v[202:205], v[72:75]
	v_mfma_f32_16x16x32_bf16 v[124:127], v[132:135], v[174:177], v[124:127]
	v_mfma_f32_16x16x32_bf16 v[120:123], v[140:143], v[174:177], v[120:123]
	v_mfma_f32_16x16x32_bf16 v[108:111], v[132:135], v[184:187], v[108:111]
	v_mfma_f32_16x16x32_bf16 v[104:107], v[140:143], v[184:187], v[104:107]
	v_mfma_f32_16x16x32_bf16 v[92:95], v[132:135], v[198:201], v[92:95]
	v_mfma_f32_16x16x32_bf16 v[88:91], v[140:143], v[198:201], v[88:91]
	v_mfma_f32_16x16x32_bf16 v[76:79], v[132:135], v[206:209], v[76:79]
	v_mfma_f32_16x16x32_bf16 v[72:75], v[140:143], v[206:209], v[72:75]
	v_mfma_f32_16x16x32_bf16 v[116:119], v[144:147], v[170:173], v[116:119]
	v_mfma_f32_16x16x32_bf16 v[112:115], v[152:155], v[170:173], v[112:115]
	v_mfma_f32_16x16x32_bf16 v[100:103], v[144:147], v[178:181], v[100:103]
	v_mfma_f32_16x16x32_bf16 v[96:99], v[152:155], v[178:181], v[96:99]
	v_mfma_f32_16x16x32_bf16 v[84:87], v[144:147], v[188:191], v[84:87]
	v_mfma_f32_16x16x32_bf16 v[80:83], v[152:155], v[188:191], v[80:83]
	v_mfma_f32_16x16x32_bf16 v[68:71], v[144:147], v[202:205], v[68:71]
	v_mfma_f32_16x16x32_bf16 v[64:67], v[152:155], v[202:205], v[64:67]
	v_mfma_f32_16x16x32_bf16 v[116:119], v[148:151], v[174:177], v[116:119]
	v_mfma_f32_16x16x32_bf16 v[112:115], v[166:169], v[174:177], v[112:115]
	v_mfma_f32_16x16x32_bf16 v[100:103], v[148:151], v[184:187], v[100:103]
	v_mfma_f32_16x16x32_bf16 v[96:99], v[166:169], v[184:187], v[96:99]
	v_mfma_f32_16x16x32_bf16 v[84:87], v[148:151], v[198:201], v[84:87]
	v_mfma_f32_16x16x32_bf16 v[80:83], v[166:169], v[198:201], v[80:83]
	v_mfma_f32_16x16x32_bf16 v[68:71], v[148:151], v[206:209], v[68:71]
	v_mfma_f32_16x16x32_bf16 v[64:67], v[166:169], v[206:209], v[64:67]
	s_barrier
	s_setprio 1
	s_add_i32 s2, s30, s19
	s_mov_b32 m0, s2
	ds_read_b128 v[170:173], v183 offset:16384
	ds_read_b128 v[174:177], v183 offset:17408
	ds_read_b128 v[178:181], v183 offset:18432
	ds_read_b128 v[184:187], v183 offset:19456
	ds_read_b128 v[188:191], v183 offset:20480
	ds_read_b128 v[198:201], v183 offset:21504
	ds_read_b128 v[202:205], v183 offset:22528
	ds_read_b128 v[206:209], v183 offset:23552
	global_load_lds_dwordx4 v192, s[84:85]
	s_add_i32 m0, s2, 0x2000
	s_add_u32 s2, s84, 0x40000
	s_addc_u32 s3, s85, 0
	s_add_i32 s30, s31, s19
	global_load_lds_dwordx4 v156, s[84:85]
	s_mov_b32 m0, s30
	s_nop 0
	global_load_lds_dwordx4 v192, s[2:3]
	s_add_i32 m0, s30, 0x2000
	s_nop 0
	global_load_lds_dwordx4 v156, s[2:3]
	s_mov_b32 m0, s20
	s_nop 0
	global_load_lds_dwordx4 v160, s[86:87]
	s_mov_b32 m0, s21
	s_nop 0
	global_load_lds_dwordx4 v158, s[86:87]
	s_waitcnt vmcnt(8)
	s_waitcnt lgkmcnt(0)
	s_barrier
	s_setprio 0
	s_waitcnt lgkmcnt(0)
	v_mfma_f32_16x16x32_bf16 v[60:63], v[128:131], v[170:173], v[60:63]
	v_mfma_f32_16x16x32_bf16 v[56:59], v[136:139], v[170:173], v[56:59]
	v_mfma_f32_16x16x32_bf16 v[44:47], v[128:131], v[178:181], v[44:47]
	v_mfma_f32_16x16x32_bf16 v[40:43], v[136:139], v[178:181], v[40:43]
	v_mfma_f32_16x16x32_bf16 v[28:31], v[128:131], v[188:191], v[28:31]
	v_mfma_f32_16x16x32_bf16 v[24:27], v[136:139], v[188:191], v[24:27]
	v_mfma_f32_16x16x32_bf16 v[12:15], v[128:131], v[202:205], v[12:15]
	v_mfma_f32_16x16x32_bf16 v[8:11], v[136:139], v[202:205], v[8:11]
	v_mfma_f32_16x16x32_bf16 v[60:63], v[132:135], v[174:177], v[60:63]
	v_mfma_f32_16x16x32_bf16 v[56:59], v[140:143], v[174:177], v[56:59]
	v_mfma_f32_16x16x32_bf16 v[44:47], v[132:135], v[184:187], v[44:47]
	v_mfma_f32_16x16x32_bf16 v[40:43], v[140:143], v[184:187], v[40:43]
	v_mfma_f32_16x16x32_bf16 v[28:31], v[132:135], v[198:201], v[28:31]
	v_mfma_f32_16x16x32_bf16 v[24:27], v[140:143], v[198:201], v[24:27]
	v_mfma_f32_16x16x32_bf16 v[12:15], v[132:135], v[206:209], v[12:15]
	v_mfma_f32_16x16x32_bf16 v[8:11], v[140:143], v[206:209], v[8:11]
	v_mfma_f32_16x16x32_bf16 v[52:55], v[144:147], v[170:173], v[52:55]
	v_mfma_f32_16x16x32_bf16 v[48:51], v[152:155], v[170:173], v[48:51]
	v_mfma_f32_16x16x32_bf16 v[36:39], v[144:147], v[178:181], v[36:39]
	v_mfma_f32_16x16x32_bf16 v[32:35], v[152:155], v[178:181], v[32:35]
	v_mfma_f32_16x16x32_bf16 v[20:23], v[144:147], v[188:191], v[20:23]
	v_mfma_f32_16x16x32_bf16 v[16:19], v[152:155], v[188:191], v[16:19]
	v_mfma_f32_16x16x32_bf16 v[4:7], v[144:147], v[202:205], v[4:7]
	v_mfma_f32_16x16x32_bf16 v[0:3], v[152:155], v[202:205], v[0:3]
	v_mfma_f32_16x16x32_bf16 v[52:55], v[148:151], v[174:177], v[52:55]
	v_mfma_f32_16x16x32_bf16 v[48:51], v[166:169], v[174:177], v[48:51]
	v_mfma_f32_16x16x32_bf16 v[36:39], v[148:151], v[184:187], v[36:39]
	v_mfma_f32_16x16x32_bf16 v[32:35], v[166:169], v[184:187], v[32:35]
	v_mfma_f32_16x16x32_bf16 v[20:23], v[148:151], v[198:201], v[20:23]
	v_mfma_f32_16x16x32_bf16 v[16:19], v[166:169], v[198:201], v[16:19]
	v_mfma_f32_16x16x32_bf16 v[4:7], v[148:151], v[206:209], v[4:7]
	v_mfma_f32_16x16x32_bf16 v[0:3], v[166:169], v[206:209], v[0:3]
	s_barrier
; #define PG8_STAGE(bufoff, gbase, voff) do { _Pragma("unroll") for (int _i = 0; _i < 2; ++_i) \
;         __builtin_amdgcn_global_load_lds((const unsigned*)((const char*)(gbase) + (voff)[_i]), (PG8_LAS unsigned*)(lds + (bufoff) + ldsw + _i * 8192), 16, 0, 0); } while (0)
; #define PG8_LDA(dst, b, h) do { _Pragma("unroll") for (int m = 0; m < 4; ++m) _Pragma("unroll") for (int k = 0; k < 2; ++k) dst[m][k] = *(const PG8_LAS bf16x8*)(lds + PG8_SA(b, h) + aoff + m * 2048 + k * 1024); } while (0)
; #define PG8_LDB(dst, b, h) do { _Pragma("unroll") for (int n = 0; n < 2; ++n) _Pragma("unroll") for (int k = 0; k < 2; ++k) dst[n][k] = *(const PG8_LAS bf16x8*)(lds + PG8_SB(b, h) + boff + n * 2048 + k * 1024); } while (0)
; #define PG8_MMA(ai, bj, At, Bt) do { __builtin_amdgcn_s_setprio(1); _Pragma("unroll") for (int m = 0; m < 4; ++m) _Pragma("unroll") for (int n = 0; n < 2; ++n) _Pragma("unroll") for (int k = 0; k < 2; ++k) \
;         acc[ai][bj][m][n] = __builtin_amdgcn_mfma_f32_16x16x32_bf16(Bt[n][k], At[m][k], acc[ai][bj][m][n], 0, 0, 0); __builtin_amdgcn_s_setprio(0); } while (0)
; #define PG8_WAIT_V(n) asm volatile("s_waitcnt vmcnt(" #n ")" ::: "memory")
; #define PG8_WAIT_L(n) asm volatile("s_waitcnt lgkmcnt(" #n ")" ::: "memory")
; #define PG8_BAR __builtin_amdgcn_s_barrier()
; #define PG8_SCHED __builtin_amdgcn_sched_barrier(0)
; template <class Epi, class Sched, bool ALIGN_EPI = false, bool SP2 = false>
; __device__ __forceinline__ void gemm_phase(PG8_LAS unsigned char* lds, const Gemm g, const Sched& S, const Epi& E) {
;     ...
;             PG8_LDB(B0, 1, 0); PG8_LDB(B1, 1, 1); PG8_SCHED; PG8_LDA(At, 1, 0); PG8_STAGE(PG8_SA(0, 1), a2 + hstepA, voffA);
;             PG8_WAIT_V(8); PG8_WAIT_L(0); PG8_BAR; PG8_MMA(0, 0, At, B0); PG8_MMA(0, 1, At, B1); PG8_BAR; PG8_SCHED;
;             PG8_LDA(At, 1, 1); PG8_STAGE(PG8_SB(1, 0), b3, voffB); PG8_STAGE(PG8_SB(1, 1), b3 + hstepB, voffB); PG8_STAGE(PG8_SA(1, 0), a3, voffA);
;             PG8_WAIT_V(8); PG8_WAIT_L(0); PG8_BAR; PG8_MMA(1, 0, At, B0); PG8_MMA(1, 1, At, B1); PG8_BAR; PG8_SCHED;
	s_setprio 1
	s_add_i32 s30, 0, 0x18000
	s_add_i32 s31, 0, 0x1c000
	v_add_u32_e32 v140, s30, v182
	v_add_u32_e32 v166, s31, v182
	ds_read_b128 v[128:131], v140
	ds_read_b128 v[132:135], v140 offset:1024
	ds_read_b128 v[136:139], v140 offset:2048
	ds_read_b128 v[140:143], v140 offset:3072
	ds_read_b128 v[144:147], v166
	ds_read_b128 v[148:151], v166 offset:1024
	ds_read_b128 v[152:155], v166 offset:2048
	ds_read_b128 v[166:169], v166 offset:3072
	s_add_u32 s2, s86, 0x40000
	s_addc_u32 s3, s87, 0
	s_mov_b32 m0, s34
	ds_read_b128 v[170:173], v183 offset:32768
	ds_read_b128 v[174:177], v183 offset:33792
	ds_read_b128 v[178:181], v183 offset:34816
	ds_read_b128 v[184:187], v183 offset:35840
	ds_read_b128 v[188:191], v183 offset:36864
	ds_read_b128 v[198:201], v183 offset:37888
	ds_read_b128 v[202:205], v183 offset:38912
	ds_read_b128 v[206:209], v183 offset:39936
	global_load_lds_dwordx4 v160, s[2:3]
	s_mov_b32 m0, s45
	s_nop 0
	global_load_lds_dwordx4 v158, s[2:3]
	s_waitcnt vmcnt(8)
	s_waitcnt lgkmcnt(0)
	s_barrier
	s_setprio 0
	s_waitcnt lgkmcnt(0)
	v_mfma_f32_16x16x32_bf16 v[124:127], v[128:131], v[170:173], v[124:127]
	v_mfma_f32_16x16x32_bf16 v[120:123], v[136:139], v[170:173], v[120:123]
	v_mfma_f32_16x16x32_bf16 v[108:111], v[128:131], v[178:181], v[108:111]
	v_mfma_f32_16x16x32_bf16 v[104:107], v[136:139], v[178:181], v[104:107]
	v_mfma_f32_16x16x32_bf16 v[92:95], v[128:131], v[188:191], v[92:95]
	v_mfma_f32_16x16x32_bf16 v[88:91], v[136:139], v[188:191], v[88:91]
	v_mfma_f32_16x16x32_bf16 v[76:79], v[128:131], v[202:205], v[76:79]
	v_mfma_f32_16x16x32_bf16 v[72:75], v[136:139], v[202:205], v[72:75]
	v_mfma_f32_16x16x32_bf16 v[124:127], v[132:135], v[174:177], v[124:127]
	v_mfma_f32_16x16x32_bf16 v[120:123], v[140:143], v[174:177], v[120:123]
	v_mfma_f32_16x16x32_bf16 v[108:111], v[132:135], v[184:187], v[108:111]
	v_mfma_f32_16x16x32_bf16 v[104:107], v[140:143], v[184:187], v[104:107]
	v_mfma_f32_16x16x32_bf16 v[92:95], v[132:135], v[198:201], v[92:95]
	v_mfma_f32_16x16x32_bf16 v[88:91], v[140:143], v[198:201], v[88:91]
	v_mfma_f32_16x16x32_bf16 v[76:79], v[132:135], v[206:209], v[76:79]
	v_mfma_f32_16x16x32_bf16 v[72:75], v[140:143], v[206:209], v[72:75]
	v_mfma_f32_16x16x32_bf16 v[116:119], v[144:147], v[170:173], v[116:119]
	v_mfma_f32_16x16x32_bf16 v[112:115], v[152:155], v[170:173], v[112:115]
	v_mfma_f32_16x16x32_bf16 v[100:103], v[144:147], v[178:181], v[100:103]
	v_mfma_f32_16x16x32_bf16 v[96:99], v[152:155], v[178:181], v[96:99]
	v_mfma_f32_16x16x32_bf16 v[84:87], v[144:147], v[188:191], v[84:87]
	v_mfma_f32_16x16x32_bf16 v[80:83], v[152:155], v[188:191], v[80:83]
	v_mfma_f32_16x16x32_bf16 v[68:71], v[144:147], v[202:205], v[68:71]
	v_mfma_f32_16x16x32_bf16 v[64:67], v[152:155], v[202:205], v[64:67]
	v_mfma_f32_16x16x32_bf16 v[116:119], v[148:151], v[174:177], v[116:119]
	v_mfma_f32_16x16x32_bf16 v[112:115], v[166:169], v[174:177], v[112:115]
	v_mfma_f32_16x16x32_bf16 v[100:103], v[148:151], v[184:187], v[100:103]
	v_mfma_f32_16x16x32_bf16 v[96:99], v[166:169], v[184:187], v[96:99]
	v_mfma_f32_16x16x32_bf16 v[84:87], v[148:151], v[198:201], v[84:87]
	v_mfma_f32_16x16x32_bf16 v[80:83], v[166:169], v[198:201], v[80:83]
	v_mfma_f32_16x16x32_bf16 v[68:71], v[148:151], v[206:209], v[68:71]
	v_mfma_f32_16x16x32_bf16 v[64:67], v[166:169], v[206:209], v[64:67]
	s_barrier
	s_setprio 1
	s_add_i32 s2, s30, s19
	s_add_i32 m0, s2, 0xffffff80
	ds_read_b128 v[170:173], v183 offset:49152
	ds_read_b128 v[174:177], v183 offset:50176
	ds_read_b128 v[178:181], v183 offset:51200
	ds_read_b128 v[184:187], v183 offset:52224
	ds_read_b128 v[188:191], v183 offset:53248
	ds_read_b128 v[198:201], v183 offset:54272
	ds_read_b128 v[202:205], v183 offset:55296
	ds_read_b128 v[206:209], v183 offset:56320
	global_load_lds_dwordx4 v192, s[84:85] offset:128
	s_add_i32 m0, s2, 0x1f80
	s_add_u32 s2, s84, 0x40080
	s_addc_u32 s3, s85, 0
	s_add_i32 s30, s31, s19
	global_load_lds_dwordx4 v156, s[84:85] offset:128
	s_mov_b32 m0, s30
	s_nop 0
	global_load_lds_dwordx4 v192, s[2:3]
	s_add_i32 m0, s30, 0x2000
	s_nop 0
	global_load_lds_dwordx4 v156, s[2:3]
	s_add_i32 m0, s63, 0xffffff80
	s_nop 0
	global_load_lds_dwordx4 v160, s[86:87] offset:128
	s_add_i32 m0, s64, 0xffffff80
	s_nop 0
	global_load_lds_dwordx4 v158, s[86:87] offset:128
	s_waitcnt vmcnt(8)
	s_waitcnt lgkmcnt(0)
	s_barrier
	s_setprio 0
	s_waitcnt lgkmcnt(0)
	v_mfma_f32_16x16x32_bf16 v[60:63], v[128:131], v[170:173], v[60:63]
	v_mfma_f32_16x16x32_bf16 v[56:59], v[136:139], v[170:173], v[56:59]
	v_mfma_f32_16x16x32_bf16 v[44:47], v[128:131], v[178:181], v[44:47]
	v_mfma_f32_16x16x32_bf16 v[40:43], v[136:139], v[178:181], v[40:43]
	v_mfma_f32_16x16x32_bf16 v[28:31], v[128:131], v[188:191], v[28:31]
	v_mfma_f32_16x16x32_bf16 v[24:27], v[136:139], v[188:191], v[24:27]
	v_mfma_f32_16x16x32_bf16 v[12:15], v[128:131], v[202:205], v[12:15]
	v_mfma_f32_16x16x32_bf16 v[8:11], v[136:139], v[202:205], v[8:11]
	v_mfma_f32_16x16x32_bf16 v[60:63], v[132:135], v[174:177], v[60:63]
	v_mfma_f32_16x16x32_bf16 v[56:59], v[140:143], v[174:177], v[56:59]
	v_mfma_f32_16x16x32_bf16 v[44:47], v[132:135], v[184:187], v[44:47]
	v_mfma_f32_16x16x32_bf16 v[40:43], v[140:143], v[184:187], v[40:43]
	v_mfma_f32_16x16x32_bf16 v[28:31], v[132:135], v[198:201], v[28:31]
	v_mfma_f32_16x16x32_bf16 v[24:27], v[140:143], v[198:201], v[24:27]
	v_mfma_f32_16x16x32_bf16 v[12:15], v[132:135], v[206:209], v[12:15]
	v_mfma_f32_16x16x32_bf16 v[8:11], v[140:143], v[206:209], v[8:11]
	v_mfma_f32_16x16x32_bf16 v[52:55], v[144:147], v[170:173], v[52:55]
	v_mfma_f32_16x16x32_bf16 v[48:51], v[152:155], v[170:173], v[48:51]
	v_mfma_f32_16x16x32_bf16 v[36:39], v[144:147], v[178:181], v[36:39]
	v_mfma_f32_16x16x32_bf16 v[32:35], v[152:155], v[178:181], v[32:35]
	v_mfma_f32_16x16x32_bf16 v[20:23], v[144:147], v[188:191], v[20:23]
	v_mfma_f32_16x16x32_bf16 v[16:19], v[152:155], v[188:191], v[16:19]
	v_mfma_f32_16x16x32_bf16 v[4:7], v[144:147], v[202:205], v[4:7]
	v_mfma_f32_16x16x32_bf16 v[0:3], v[152:155], v[202:205], v[0:3]
	v_mfma_f32_16x16x32_bf16 v[52:55], v[148:151], v[174:177], v[52:55]
	v_mfma_f32_16x16x32_bf16 v[48:51], v[166:169], v[174:177], v[48:51]
	v_mfma_f32_16x16x32_bf16 v[36:39], v[148:151], v[184:187], v[36:39]
	v_mfma_f32_16x16x32_bf16 v[32:35], v[166:169], v[184:187], v[32:35]
	v_mfma_f32_16x16x32_bf16 v[20:23], v[148:151], v[198:201], v[20:23]
	v_mfma_f32_16x16x32_bf16 v[16:19], v[166:169], v[198:201], v[16:19]
	v_mfma_f32_16x16x32_bf16 v[4:7], v[148:151], v[206:209], v[4:7]
	v_mfma_f32_16x16x32_bf16 v[0:3], v[166:169], v[206:209], v[0:3]
	s_barrier
	s_setprio 1
	s_add_i32 s92, s92, 2
	s_add_u32 s90, s90, 0x100
	s_addc_u32 s91, s91, 0
	s_add_u32 s4, s4, 0x100
	s_addc_u32 s5, s5, 0
	s_cmp_gt_u32 s92, 13
	s_cbranch_scc0 .LBB0_693
	s_and_b64 vcc, exec, s[12:13]
	s_cbranch_vccz .LBB0_696
	s_barrier

; #define PG8_STAGE(bufoff, gbase, voff) do { _Pragma("unroll") for (int _i = 0; _i < 2; ++_i) \
;         __builtin_amdgcn_global_load_lds((const unsigned*)((const char*)(gbase) + (voff)[_i]), (PG8_LAS unsigned*)(lds + (bufoff) + ldsw + _i * 8192), 16, 0, 0); } while (0)
; #define PG8_LDA(dst, b, h) do { _Pragma("unroll") for (int m = 0; m < 4; ++m) _Pragma("unroll") for (int k = 0; k < 2; ++k) dst[m][k] = *(const PG8_LAS bf16x8*)(lds + PG8_SA(b, h) + aoff + m * 2048 + k * 1024); } while (0)
; #define PG8_LDB(dst, b, h) do { _Pragma("unroll") for (int n = 0; n < 2; ++n) _Pragma("unroll") for (int k = 0; k < 2; ++k) dst[n][k] = *(const PG8_LAS bf16x8*)(lds + PG8_SB(b, h) + boff + n * 2048 + k * 1024); } while (0)
; #define PG8_MMA(ai, bj, At, Bt) do { __builtin_amdgcn_s_setprio(1); _Pragma("unroll") for (int m = 0; m < 4; ++m) _Pragma("unroll") for (int n = 0; n < 2; ++n) _Pragma("unroll") for (int k = 0; k < 2; ++k) \
;         acc[ai][bj][m][n] = __builtin_amdgcn_mfma_f32_16x16x32_bf16(Bt[n][k], At[m][k], acc[ai][bj][m][n], 0, 0, 0); __builtin_amdgcn_s_setprio(0); } while (0)
; #define PG8_WAIT_V(n) asm volatile("s_waitcnt vmcnt(" #n ")" ::: "memory")
; #define PG8_WAIT_L(n) asm volatile("s_waitcnt lgkmcnt(" #n ")" ::: "memory")
; #define PG8_BAR __builtin_amdgcn_s_barrier()
; template <class Epi, class Sched, bool ALIGN_EPI = false, bool SP2 = false>
; __device__ __forceinline__ void gemm_phase(PG8_LAS unsigned char* lds, const Gemm g, const Sched& S, const Epi& E) {
;     ...
;             const char* a1 = cA + (size_t)(t + 1) * kstep;
;             const char* a2 = last ? nA : cA + (size_t)(t + 2) * kstep; const char* b2 = last ? nB : cB + (size_t)(t + 2) * kstep;
;             const char* a3 = a2 + kstep; const char* b3 = b2 + kstep;
;             if (last && has_next) S.a_ready(nxt);
;             if constexpr (SP2) {
;             PG8_LDB(B0, 0, 0); PG8_LDB(B1, 0, 1); PG8_SCHED; PG8_LDA(At, 0, 0); PG8_STAGE(PG8_SA(1, 1), a1 + hstepA, voffA);
;             PG8_WAIT_V(8); PG8_WAIT_L(0); PG8_BAR; PG8_MMA(0, 0, At, B0); PG8_MMA(0, 1, At, B1); PG8_BAR; PG8_SCHED;
;             PG8_LDA(At, 0, 1); PG8_STAGE(PG8_SB(0, 0), b2, voffB); PG8_STAGE(PG8_SB(0, 1), b2 + hstepB, voffB); PG8_STAGE(PG8_SA(0, 0), a2, voffA);
;             PG8_WAIT_V(8); PG8_WAIT_L(0); PG8_BAR; PG8_MMA(1, 0, At, B0); PG8_MMA(1, 1, At, B1); PG8_BAR; PG8_SCHED;
.LBB0_724:
	s_add_i32 s2, s84, 2
	s_add_u32 s3, s82, 0x80
	s_addc_u32 s30, s83, 0
	s_add_i32 s77, 0, 0x10000
	s_cmp_eq_u32 s93, s84
	s_cselect_b32 s85, s5, s30
	s_cselect_b32 s84, s4, s3
	s_cselect_b32 s31, s67, vcc_hi
	s_cselect_b32 s30, s66, vcc_lo
	s_add_i32 s3, 0, 0x14000
	v_add_u32_e32 v136, s77, v247
	v_add_u32_e32 v156, s3, v247
	ds_read_b128 v[112:115], v136
	ds_read_b128 v[124:127], v136 offset:1024
	ds_read_b128 v[128:131], v136 offset:2048
	ds_read_b128 v[136:139], v136 offset:3072
	ds_read_b128 v[144:147], v156
	ds_read_b128 v[148:151], v156 offset:1024
	ds_read_b128 v[152:155], v156 offset:2048
	ds_read_b128 v[156:159], v156 offset:3072
	s_add_i32 m0, s64, 0xc000
	ds_read_b128 v[160:163], v248
	ds_read_b128 v[164:167], v248 offset:1024
	ds_read_b128 v[168:171], v248 offset:2048
	ds_read_b128 v[172:175], v248 offset:3072
	ds_read_b128 v[176:179], v248 offset:4096
	ds_read_b128 v[180:183], v248 offset:5120
	ds_read_b128 v[184:187], v248 offset:6144
	ds_read_b128 v[188:191], v248 offset:7168
	global_load_lds_dwordx4 v206, s[82:83]
	s_add_i32 m0, s64, 0xe000
	s_nop 0
	global_load_lds_dwordx4 v204, s[82:83]
	s_waitcnt vmcnt(8)
	s_waitcnt lgkmcnt(0)
	s_barrier
	s_setprio 0
	s_waitcnt lgkmcnt(0)
	v_mfma_f32_16x16x32_bf16 v[140:143], v[112:115], v[160:163], v[140:143]
	v_mfma_f32_16x16x32_bf16 v[132:135], v[128:131], v[160:163], v[132:135]
	v_mfma_f32_16x16x32_bf16 v[108:111], v[112:115], v[168:171], v[108:111]
	v_mfma_f32_16x16x32_bf16 v[104:107], v[128:131], v[168:171], v[104:107]
	v_mfma_f32_16x16x32_bf16 v[92:95], v[112:115], v[176:179], v[92:95]
	v_mfma_f32_16x16x32_bf16 v[88:91], v[128:131], v[176:179], v[88:91]
	v_mfma_f32_16x16x32_bf16 v[76:79], v[112:115], v[184:187], v[76:79]
	v_mfma_f32_16x16x32_bf16 v[72:75], v[128:131], v[184:187], v[72:75]
	v_mfma_f32_16x16x32_bf16 v[140:143], v[124:127], v[164:167], v[140:143]
	v_mfma_f32_16x16x32_bf16 v[132:135], v[136:139], v[164:167], v[132:135]
	v_mfma_f32_16x16x32_bf16 v[108:111], v[124:127], v[172:175], v[108:111]
	v_mfma_f32_16x16x32_bf16 v[104:107], v[136:139], v[172:175], v[104:107]
	v_mfma_f32_16x16x32_bf16 v[92:95], v[124:127], v[180:183], v[92:95]
	v_mfma_f32_16x16x32_bf16 v[88:91], v[136:139], v[180:183], v[88:91]
	v_mfma_f32_16x16x32_bf16 v[76:79], v[124:127], v[188:191], v[76:79]
	v_mfma_f32_16x16x32_bf16 v[72:75], v[136:139], v[188:191], v[72:75]
	v_mfma_f32_16x16x32_bf16 v[120:123], v[144:147], v[160:163], v[120:123]
	v_mfma_f32_16x16x32_bf16 v[116:119], v[152:155], v[160:163], v[116:119]
	v_mfma_f32_16x16x32_bf16 v[100:103], v[144:147], v[168:171], v[100:103]
	v_mfma_f32_16x16x32_bf16 v[96:99], v[152:155], v[168:171], v[96:99]
	v_mfma_f32_16x16x32_bf16 v[84:87], v[144:147], v[176:179], v[84:87]
	v_mfma_f32_16x16x32_bf16 v[80:83], v[152:155], v[176:179], v[80:83]
	v_mfma_f32_16x16x32_bf16 v[68:71], v[144:147], v[184:187], v[68:71]
	v_mfma_f32_16x16x32_bf16 v[64:67], v[152:155], v[184:187], v[64:67]
	v_mfma_f32_16x16x32_bf16 v[120:123], v[148:151], v[164:167], v[120:123]
	v_mfma_f32_16x16x32_bf16 v[116:119], v[156:159], v[164:167], v[116:119]
	v_mfma_f32_16x16x32_bf16 v[100:103], v[148:151], v[172:175], v[100:103]
	v_mfma_f32_16x16x32_bf16 v[96:99], v[156:159], v[172:175], v[96:99]
	v_mfma_f32_16x16x32_bf16 v[84:87], v[148:151], v[180:183], v[84:87]
	v_mfma_f32_16x16x32_bf16 v[80:83], v[156:159], v[180:183], v[80:83]
	v_mfma_f32_16x16x32_bf16 v[68:71], v[148:151], v[188:191], v[68:71]
	v_mfma_f32_16x16x32_bf16 v[64:67], v[156:159], v[188:191], v[64:67]
	s_barrier
	s_setprio 1
	s_add_i32 s77, s77, s63
	v_lshl_add_u64 v[208:209], s[30:31], 0, v[192:193]
	s_mov_b32 m0, s77
	ds_read_b128 v[160:163], v248 offset:16384
	ds_read_b128 v[164:167], v248 offset:17408
	ds_read_b128 v[168:171], v248 offset:18432
	ds_read_b128 v[172:175], v248 offset:19456
	ds_read_b128 v[176:179], v248 offset:20480
	ds_read_b128 v[180:183], v248 offset:21504
	ds_read_b128 v[184:187], v248 offset:22528
	ds_read_b128 v[188:191], v248 offset:23552
	global_load_lds_dwordx4 v192, s[30:31]
	s_add_i32 m0, s77, 0x2000
	v_lshl_add_u64 v[210:211], s[30:31], 0, v[198:199]
	global_load_lds_dwordx4 v198, s[30:31]
	s_add_u32 s30, s30, s45
	s_addc_u32 s31, s31, 0
	s_add_i32 s3, s3, s63
	v_lshl_add_u64 v[212:213], s[30:31], 0, v[192:193]
	s_mov_b32 m0, s3
	v_lshl_add_u64 v[214:215], s[30:31], 0, v[198:199]
	global_load_lds_dwordx4 v192, s[30:31]
	s_add_i32 m0, s3, 0x2000
	s_nop 0
	global_load_lds_dwordx4 v198, s[30:31]
	s_mov_b32 m0, s64
	s_nop 0
	global_load_lds_dwordx4 v202, s[84:85]
	s_mov_b32 m0, s65
	s_nop 0
	global_load_lds_dwordx4 v200, s[84:85]
	s_waitcnt vmcnt(8)
	s_waitcnt lgkmcnt(0)
	s_barrier
; #define PG8_STAGE(bufoff, gbase, voff) do { _Pragma("unroll") for (int _i = 0; _i < 2; ++_i) \
;         __builtin_amdgcn_global_load_lds((const unsigned*)((const char*)(gbase) + (voff)[_i]), (PG8_LAS unsigned*)(lds + (bufoff) + ldsw + _i * 8192), 16, 0, 0); } while (0)
; #define PG8_LDA(dst, b, h) do { _Pragma("unroll") for (int m = 0; m < 4; ++m) _Pragma("unroll") for (int k = 0; k < 2; ++k) dst[m][k] = *(const PG8_LAS bf16x8*)(lds + PG8_SA(b, h) + aoff + m * 2048 + k * 1024); } while (0)
; #define PG8_LDB(dst, b, h) do { _Pragma("unroll") for (int n = 0; n < 2; ++n) _Pragma("unroll") for (int k = 0; k < 2; ++k) dst[n][k] = *(const PG8_LAS bf16x8*)(lds + PG8_SB(b, h) + boff + n * 2048 + k * 1024); } while (0)
; #define PG8_MMA(ai, bj, At, Bt) do { __builtin_amdgcn_s_setprio(1); _Pragma("unroll") for (int m = 0; m < 4; ++m) _Pragma("unroll") for (int n = 0; n < 2; ++n) _Pragma("unroll") for (int k = 0; k < 2; ++k) \
;         acc[ai][bj][m][n] = __builtin_amdgcn_mfma_f32_16x16x32_bf16(Bt[n][k], At[m][k], acc[ai][bj][m][n], 0, 0, 0); __builtin_amdgcn_s_setprio(0); } while (0)
; #define PG8_WAIT_V(n) asm volatile("s_waitcnt vmcnt(" #n ")" ::: "memory")
; #define PG8_WAIT_L(n) asm volatile("s_waitcnt lgkmcnt(" #n ")" ::: "memory")
; #define PG8_BAR __builtin_amdgcn_s_barrier()
; #define PG8_SCHED __builtin_amdgcn_sched_barrier(0)
; template <class Epi, class Sched, bool ALIGN_EPI = false, bool SP2 = false>
; __device__ __forceinline__ void gemm_phase(PG8_LAS unsigned char* lds, const Gemm g, const Sched& S, const Epi& E) {
;     ...
;             PG8_WAIT_V(8); PG8_WAIT_L(0); PG8_BAR; PG8_MMA(1, 0, At, B0); PG8_MMA(1, 1, At, B1); PG8_BAR; PG8_SCHED;
;             PG8_LDB(B0, 1, 0); PG8_LDB(B1, 1, 1); PG8_SCHED; PG8_LDA(At, 1, 0); PG8_STAGE(PG8_SA(0, 1), a2 + hstepA, voffA);
;             PG8_WAIT_V(8); PG8_WAIT_L(0); PG8_BAR; PG8_MMA(0, 0, At, B0); PG8_MMA(0, 1, At, B1); PG8_BAR; PG8_SCHED;
	s_setprio 0
	s_waitcnt lgkmcnt(0)
	v_mfma_f32_16x16x32_bf16 v[60:63], v[112:115], v[160:163], v[60:63]
	v_mfma_f32_16x16x32_bf16 v[56:59], v[128:131], v[160:163], v[56:59]
	v_mfma_f32_16x16x32_bf16 v[44:47], v[112:115], v[168:171], v[44:47]
	v_mfma_f32_16x16x32_bf16 v[40:43], v[128:131], v[168:171], v[40:43]
	v_mfma_f32_16x16x32_bf16 v[28:31], v[112:115], v[176:179], v[28:31]
	v_mfma_f32_16x16x32_bf16 v[24:27], v[128:131], v[176:179], v[24:27]
	v_mfma_f32_16x16x32_bf16 v[12:15], v[112:115], v[184:187], v[12:15]
	v_mfma_f32_16x16x32_bf16 v[8:11], v[128:131], v[184:187], v[8:11]
	v_mfma_f32_16x16x32_bf16 v[60:63], v[124:127], v[164:167], v[60:63]
	v_mfma_f32_16x16x32_bf16 v[56:59], v[136:139], v[164:167], v[56:59]
	v_mfma_f32_16x16x32_bf16 v[44:47], v[124:127], v[172:175], v[44:47]
	v_mfma_f32_16x16x32_bf16 v[40:43], v[136:139], v[172:175], v[40:43]
	v_mfma_f32_16x16x32_bf16 v[28:31], v[124:127], v[180:183], v[28:31]
	v_mfma_f32_16x16x32_bf16 v[24:27], v[136:139], v[180:183], v[24:27]
	v_mfma_f32_16x16x32_bf16 v[12:15], v[124:127], v[188:191], v[12:15]
	v_mfma_f32_16x16x32_bf16 v[8:11], v[136:139], v[188:191], v[8:11]
	v_mfma_f32_16x16x32_bf16 v[52:55], v[144:147], v[160:163], v[52:55]
	v_mfma_f32_16x16x32_bf16 v[48:51], v[152:155], v[160:163], v[48:51]
	v_mfma_f32_16x16x32_bf16 v[36:39], v[144:147], v[168:171], v[36:39]
	v_mfma_f32_16x16x32_bf16 v[32:35], v[152:155], v[168:171], v[32:35]
	v_mfma_f32_16x16x32_bf16 v[20:23], v[144:147], v[176:179], v[20:23]
	v_mfma_f32_16x16x32_bf16 v[16:19], v[152:155], v[176:179], v[16:19]
	v_mfma_f32_16x16x32_bf16 v[4:7], v[144:147], v[184:187], v[4:7]
	v_mfma_f32_16x16x32_bf16 v[0:3], v[152:155], v[184:187], v[0:3]
	v_mfma_f32_16x16x32_bf16 v[52:55], v[148:151], v[164:167], v[52:55]
	v_mfma_f32_16x16x32_bf16 v[48:51], v[156:159], v[164:167], v[48:51]
	v_mfma_f32_16x16x32_bf16 v[36:39], v[148:151], v[172:175], v[36:39]
	v_mfma_f32_16x16x32_bf16 v[32:35], v[156:159], v[172:175], v[32:35]
	v_mfma_f32_16x16x32_bf16 v[20:23], v[148:151], v[180:183], v[20:23]
	v_mfma_f32_16x16x32_bf16 v[16:19], v[156:159], v[180:183], v[16:19]
	v_mfma_f32_16x16x32_bf16 v[4:7], v[148:151], v[188:191], v[4:7]
	v_mfma_f32_16x16x32_bf16 v[0:3], v[156:159], v[188:191], v[0:3]
	s_barrier
	s_setprio 1
	s_add_i32 s3, 0, 0x18000
	s_add_i32 s77, 0, 0x1c000
	v_add_u32_e32 v136, s3, v247
	v_add_u32_e32 v156, s77, v247
	ds_read_b128 v[112:115], v136
	ds_read_b128 v[124:127], v136 offset:1024
	ds_read_b128 v[128:131], v136 offset:2048
	ds_read_b128 v[136:139], v136 offset:3072
	ds_read_b128 v[144:147], v156
	ds_read_b128 v[148:151], v156 offset:1024
	ds_read_b128 v[152:155], v156 offset:2048
	ds_read_b128 v[156:159], v156 offset:3072
	s_add_u32 s30, s84, s10
	s_addc_u32 s31, s85, 0
	s_mov_b32 m0, s80
	ds_read_b128 v[160:163], v248 offset:32768
	ds_read_b128 v[164:167], v248 offset:33792
	ds_read_b128 v[168:171], v248 offset:34816
	ds_read_b128 v[172:175], v248 offset:35840
	ds_read_b128 v[176:179], v248 offset:36864
	ds_read_b128 v[180:183], v248 offset:37888
	ds_read_b128 v[184:187], v248 offset:38912
	ds_read_b128 v[188:191], v248 offset:39936
	global_load_lds_dwordx4 v202, s[30:31]
	s_mov_b32 m0, s86
	s_nop 0
	global_load_lds_dwordx4 v200, s[30:31]
	s_waitcnt vmcnt(8)
	s_waitcnt lgkmcnt(0)
	s_barrier
	s_setprio 0
	s_waitcnt lgkmcnt(0)
	v_mfma_f32_16x16x32_bf16 v[140:143], v[112:115], v[160:163], v[140:143]
	v_mfma_f32_16x16x32_bf16 v[132:135], v[128:131], v[160:163], v[132:135]
	v_mfma_f32_16x16x32_bf16 v[108:111], v[112:115], v[168:171], v[108:111]
	v_mfma_f32_16x16x32_bf16 v[104:107], v[128:131], v[168:171], v[104:107]
	v_mfma_f32_16x16x32_bf16 v[92:95], v[112:115], v[176:179], v[92:95]
	v_mfma_f32_16x16x32_bf16 v[88:91], v[128:131], v[176:179], v[88:91]
	v_mfma_f32_16x16x32_bf16 v[76:79], v[112:115], v[184:187], v[76:79]
	v_mfma_f32_16x16x32_bf16 v[72:75], v[128:131], v[184:187], v[72:75]
	v_mfma_f32_16x16x32_bf16 v[140:143], v[124:127], v[164:167], v[140:143]
	v_mfma_f32_16x16x32_bf16 v[132:135], v[136:139], v[164:167], v[132:135]
	v_mfma_f32_16x16x32_bf16 v[108:111], v[124:127], v[172:175], v[108:111]
	v_mfma_f32_16x16x32_bf16 v[104:107], v[136:139], v[172:175], v[104:107]
	v_mfma_f32_16x16x32_bf16 v[92:95], v[124:127], v[180:183], v[92:95]
	v_mfma_f32_16x16x32_bf16 v[88:91], v[136:139], v[180:183], v[88:91]
	v_mfma_f32_16x16x32_bf16 v[76:79], v[124:127], v[188:191], v[76:79]
	v_mfma_f32_16x16x32_bf16 v[72:75], v[136:139], v[188:191], v[72:75]
	v_mfma_f32_16x16x32_bf16 v[120:123], v[144:147], v[160:163], v[120:123]
	v_mfma_f32_16x16x32_bf16 v[116:119], v[152:155], v[160:163], v[116:119]
	v_mfma_f32_16x16x32_bf16 v[100:103], v[144:147], v[168:171], v[100:103]
	v_mfma_f32_16x16x32_bf16 v[96:99], v[152:155], v[168:171], v[96:99]
	v_mfma_f32_16x16x32_bf16 v[84:87], v[144:147], v[176:179], v[84:87]
	v_mfma_f32_16x16x32_bf16 v[80:83], v[152:155], v[176:179], v[80:83]
	v_mfma_f32_16x16x32_bf16 v[68:71], v[144:147], v[184:187], v[68:71]
	v_mfma_f32_16x16x32_bf16 v[64:67], v[152:155], v[184:187], v[64:67]
	v_mfma_f32_16x16x32_bf16 v[120:123], v[148:151], v[164:167], v[120:123]
	v_mfma_f32_16x16x32_bf16 v[116:119], v[156:159], v[164:167], v[116:119]
	v_mfma_f32_16x16x32_bf16 v[100:103], v[148:151], v[172:175], v[100:103]
	v_mfma_f32_16x16x32_bf16 v[96:99], v[156:159], v[172:175], v[96:99]
	v_mfma_f32_16x16x32_bf16 v[84:87], v[148:151], v[180:183], v[84:87]
	v_mfma_f32_16x16x32_bf16 v[80:83], v[156:159], v[180:183], v[80:83]
	v_mfma_f32_16x16x32_bf16 v[68:71], v[148:151], v[188:191], v[68:71]
	v_mfma_f32_16x16x32_bf16 v[64:67], v[156:159], v[188:191], v[64:67]
	s_barrier
; #define PG8_STAGE(bufoff, gbase, voff) do { _Pragma("unroll") for (int _i = 0; _i < 2; ++_i) \
;         __builtin_amdgcn_global_load_lds((const unsigned*)((const char*)(gbase) + (voff)[_i]), (PG8_LAS unsigned*)(lds + (bufoff) + ldsw + _i * 8192), 16, 0, 0); } while (0)
; #define PG8_LDA(dst, b, h) do { _Pragma("unroll") for (int m = 0; m < 4; ++m) _Pragma("unroll") for (int k = 0; k < 2; ++k) dst[m][k] = *(const PG8_LAS bf16x8*)(lds + PG8_SA(b, h) + aoff + m * 2048 + k * 1024); } while (0)
; #define PG8_MMA(ai, bj, At, Bt) do { __builtin_amdgcn_s_setprio(1); _Pragma("unroll") for (int m = 0; m < 4; ++m) _Pragma("unroll") for (int n = 0; n < 2; ++n) _Pragma("unroll") for (int k = 0; k < 2; ++k) \
;         acc[ai][bj][m][n] = __builtin_amdgcn_mfma_f32_16x16x32_bf16(Bt[n][k], At[m][k], acc[ai][bj][m][n], 0, 0, 0); __builtin_amdgcn_s_setprio(0); } while (0)
; #define PG8_WAIT_V(n) asm volatile("s_waitcnt vmcnt(" #n ")" ::: "memory")
; #define PG8_WAIT_L(n) asm volatile("s_waitcnt lgkmcnt(" #n ")" ::: "memory")
; #define PG8_BAR __builtin_amdgcn_s_barrier()
; #define PG8_SCHED __builtin_amdgcn_sched_barrier(0)
; template <class Epi, class Sched, bool ALIGN_EPI = false, bool SP2 = false>
; __device__ __forceinline__ void gemm_phase(PG8_LAS unsigned char* lds, const Gemm g, const Sched& S, const Epi& E) {
;     ...
;         for (int t = 0; t < nt; t += 2) {
;             const bool last = (t == nt - 2);
;             const char* a1 = cA + (size_t)(t + 1) * kstep;
;             const char* a2 = last ? nA : cA + (size_t)(t + 2) * kstep; const char* b2 = last ? nB : cB + (size_t)(t + 2) * kstep;
;     ...
;             PG8_LDA(At, 1, 1); PG8_STAGE(PG8_SB(1, 0), b3, voffB); PG8_STAGE(PG8_SB(1, 1), b3 + hstepB, voffB); PG8_STAGE(PG8_SA(1, 0), a3, voffA);
;             PG8_WAIT_V(8); PG8_WAIT_L(0); PG8_BAR; PG8_MMA(1, 0, At, B0); PG8_MMA(1, 1, At, B1); PG8_BAR; PG8_SCHED;
	s_setprio 1
	s_add_i32 s3, s3, s63
	v_lshl_add_u64 v[208:209], v[208:209], 0, s[36:37]
	s_mov_b32 m0, s3
	ds_read_b128 v[160:163], v248 offset:49152
	ds_read_b128 v[164:167], v248 offset:50176
	ds_read_b128 v[168:171], v248 offset:51200
	ds_read_b128 v[172:175], v248 offset:52224
	ds_read_b128 v[176:179], v248 offset:53248
	ds_read_b128 v[180:183], v248 offset:54272
	ds_read_b128 v[184:187], v248 offset:55296
	ds_read_b128 v[188:191], v248 offset:56320
	global_load_lds_dwordx4 v[208:209], off
	v_lshl_add_u64 v[208:209], v[210:211], 0, s[36:37]
	s_add_i32 m0, s3, 0x2000
	s_add_i32 s3, s77, s63
	global_load_lds_dwordx4 v[208:209], off
	v_lshl_add_u64 v[208:209], v[212:213], 0, s[36:37]
	s_mov_b32 m0, s3
	s_nop 0
	global_load_lds_dwordx4 v[208:209], off
	v_lshl_add_u64 v[208:209], v[214:215], 0, s[36:37]
	s_add_i32 m0, s3, 0x2000
	s_nop 0
	global_load_lds_dwordx4 v[208:209], off
	s_add_i32 m0, s91, 0xffffff80
	s_nop 0
	global_load_lds_dwordx4 v202, s[84:85] offset:128
	s_add_i32 m0, s92, 0xffffff80
	s_nop 0
	global_load_lds_dwordx4 v200, s[84:85] offset:128
	s_waitcnt vmcnt(8)
	s_waitcnt lgkmcnt(0)
	s_barrier
	s_setprio 0
	s_waitcnt lgkmcnt(0)
	v_mfma_f32_16x16x32_bf16 v[60:63], v[112:115], v[160:163], v[60:63]
	v_mfma_f32_16x16x32_bf16 v[56:59], v[128:131], v[160:163], v[56:59]
	v_mfma_f32_16x16x32_bf16 v[44:47], v[112:115], v[168:171], v[44:47]
	v_mfma_f32_16x16x32_bf16 v[40:43], v[128:131], v[168:171], v[40:43]
	v_mfma_f32_16x16x32_bf16 v[28:31], v[112:115], v[176:179], v[28:31]
	v_mfma_f32_16x16x32_bf16 v[24:27], v[128:131], v[176:179], v[24:27]
	v_mfma_f32_16x16x32_bf16 v[12:15], v[112:115], v[184:187], v[12:15]
	v_mfma_f32_16x16x32_bf16 v[8:11], v[128:131], v[184:187], v[8:11]
	v_mfma_f32_16x16x32_bf16 v[60:63], v[124:127], v[164:167], v[60:63]
	v_mfma_f32_16x16x32_bf16 v[56:59], v[136:139], v[164:167], v[56:59]
	v_mfma_f32_16x16x32_bf16 v[44:47], v[124:127], v[172:175], v[44:47]
	v_mfma_f32_16x16x32_bf16 v[40:43], v[136:139], v[172:175], v[40:43]
	v_mfma_f32_16x16x32_bf16 v[28:31], v[124:127], v[180:183], v[28:31]
	v_mfma_f32_16x16x32_bf16 v[24:27], v[136:139], v[180:183], v[24:27]
	v_mfma_f32_16x16x32_bf16 v[12:15], v[124:127], v[188:191], v[12:15]
	v_mfma_f32_16x16x32_bf16 v[8:11], v[136:139], v[188:191], v[8:11]
	v_mfma_f32_16x16x32_bf16 v[52:55], v[144:147], v[160:163], v[52:55]
	v_mfma_f32_16x16x32_bf16 v[48:51], v[152:155], v[160:163], v[48:51]
	v_mfma_f32_16x16x32_bf16 v[36:39], v[144:147], v[168:171], v[36:39]
	v_mfma_f32_16x16x32_bf16 v[32:35], v[152:155], v[168:171], v[32:35]
	v_mfma_f32_16x16x32_bf16 v[20:23], v[144:147], v[176:179], v[20:23]
	v_mfma_f32_16x16x32_bf16 v[16:19], v[152:155], v[176:179], v[16:19]
	v_mfma_f32_16x16x32_bf16 v[4:7], v[144:147], v[184:187], v[4:7]
	v_mfma_f32_16x16x32_bf16 v[0:3], v[152:155], v[184:187], v[0:3]
	v_mfma_f32_16x16x32_bf16 v[52:55], v[148:151], v[164:167], v[52:55]
	v_mfma_f32_16x16x32_bf16 v[48:51], v[156:159], v[164:167], v[48:51]
	v_mfma_f32_16x16x32_bf16 v[36:39], v[148:151], v[172:175], v[36:39]
	v_mfma_f32_16x16x32_bf16 v[32:35], v[156:159], v[172:175], v[32:35]
	v_mfma_f32_16x16x32_bf16 v[20:23], v[148:151], v[180:183], v[20:23]
	v_mfma_f32_16x16x32_bf16 v[16:19], v[156:159], v[180:183], v[16:19]
	v_mfma_f32_16x16x32_bf16 v[4:7], v[148:151], v[188:191], v[4:7]
	v_mfma_f32_16x16x32_bf16 v[0:3], v[156:159], v[188:191], v[0:3]
	s_barrier
	s_setprio 1
	s_add_u32 vcc_lo, vcc_lo, 0x100
	s_addc_u32 vcc_hi, vcc_hi, 0
	s_add_u32 s82, s82, 0x100
	s_addc_u32 s83, s83, 0
	s_cmp_ge_u32 s2, s87
	s_mov_b32 s84, s2
	s_cbranch_scc0 .LBB0_724
	s_and_b64 vcc, exec, s[16:17]
	s_cbranch_vccz .LBB0_727
	s_barrier

; #define PG8_STAGE(bufoff, gbase, voff) do { _Pragma("unroll") for (int _i = 0; _i < 2; ++_i) \
;         __builtin_amdgcn_global_load_lds((const unsigned*)((const char*)(gbase) + (voff)[_i]), (PG8_LAS unsigned*)(lds + (bufoff) + ldsw + _i * 8192), 16, 0, 0); } while (0)
; #define PG8_LDA(dst, b, h) do { _Pragma("unroll") for (int m = 0; m < 4; ++m) _Pragma("unroll") for (int k = 0; k < 2; ++k) dst[m][k] = *(const PG8_LAS bf16x8*)(lds + PG8_SA(b, h) + aoff + m * 2048 + k * 1024); } while (0)
; #define PG8_LDB(dst, b, h) do { _Pragma("unroll") for (int n = 0; n < 2; ++n) _Pragma("unroll") for (int k = 0; k < 2; ++k) dst[n][k] = *(const PG8_LAS bf16x8*)(lds + PG8_SB(b, h) + boff + n * 2048 + k * 1024); } while (0)
; #define PG8_MMA(ai, bj, At, Bt) do { __builtin_amdgcn_s_setprio(1); _Pragma("unroll") for (int m = 0; m < 4; ++m) _Pragma("unroll") for (int n = 0; n < 2; ++n) _Pragma("unroll") for (int k = 0; k < 2; ++k) \
;         acc[ai][bj][m][n] = __builtin_amdgcn_mfma_f32_16x16x32_bf16(Bt[n][k], At[m][k], acc[ai][bj][m][n], 0, 0, 0); __builtin_amdgcn_s_setprio(0); } while (0)
; #define PG8_WAIT_V(n) asm volatile("s_waitcnt vmcnt(" #n ")" ::: "memory")
; #define PG8_WAIT_L(n) asm volatile("s_waitcnt lgkmcnt(" #n ")" ::: "memory")
; #define PG8_BAR __builtin_amdgcn_s_barrier()
; template <class Epi, class Sched, bool ALIGN_EPI = false, bool SP2 = false>
; __device__ __forceinline__ void gemm_phase(PG8_LAS unsigned char* lds, const Gemm g, const Sched& S, const Epi& E) {
;     ...
;             const char* a1 = cA + (size_t)(t + 1) * kstep;
;             const char* a2 = last ? nA : cA + (size_t)(t + 2) * kstep; const char* b2 = last ? nB : cB + (size_t)(t + 2) * kstep;
;             const char* a3 = a2 + kstep; const char* b3 = b2 + kstep;
;             if (last && has_next) S.a_ready(nxt);
;             if constexpr (SP2) {
;             PG8_LDB(B0, 0, 0); PG8_LDB(B1, 0, 1); PG8_SCHED; PG8_LDA(At, 0, 0); PG8_STAGE(PG8_SA(1, 1), a1 + hstepA, voffA);
;             PG8_WAIT_V(8); PG8_WAIT_L(0); PG8_BAR; PG8_MMA(0, 0, At, B0); PG8_MMA(0, 1, At, B1); PG8_BAR; PG8_SCHED;
;             PG8_LDA(At, 0, 1); PG8_STAGE(PG8_SB(0, 0), b2, voffB); PG8_STAGE(PG8_SB(0, 1), b2 + hstepB, voffB); PG8_STAGE(PG8_SA(0, 0), a2, voffA);
;             PG8_WAIT_V(8); PG8_WAIT_L(0); PG8_BAR; PG8_MMA(1, 0, At, B0); PG8_MMA(1, 1, At, B1); PG8_BAR; PG8_SCHED;
.LBB0_766:
	s_add_i32 s2, s82, 2
	s_add_u32 s4, s66, 0x100
	s_addc_u32 s5, s67, 0
	s_add_i32 s3, 0, 0x10000
	s_cmp_eq_u32 s88, s82
	s_cselect_b32 s83, s15, s5
	s_cselect_b32 s82, s14, s4
	s_cselect_b32 s97, s17, s94
	s_cselect_b32 s96, s16, s93
	s_add_i32 s30, 0, 0x14000
	v_add_u32_e32 v140, s3, v222
	v_add_u32_e32 v156, s30, v222
	ds_read_b128 v[128:131], v140
	ds_read_b128 v[132:135], v140 offset:1024
	ds_read_b128 v[136:139], v140 offset:2048
	ds_read_b128 v[140:143], v140 offset:3072
	ds_read_b128 v[144:147], v156
	ds_read_b128 v[148:151], v156 offset:1024
	ds_read_b128 v[152:155], v156 offset:2048
	ds_read_b128 v[156:159], v156 offset:3072
	s_add_i32 m0, s62, 0xc000
	ds_read_b128 v[160:163], v223
	ds_read_b128 v[164:167], v223 offset:1024
	ds_read_b128 v[168:171], v223 offset:2048
	ds_read_b128 v[172:175], v223 offset:3072
	ds_read_b128 v[176:179], v223 offset:4096
	ds_read_b128 v[180:183], v223 offset:5120
	ds_read_b128 v[184:187], v223 offset:6144
	ds_read_b128 v[188:191], v223 offset:7168
	global_load_lds_dwordx4 v206, s[66:67]
	s_add_i32 m0, s62, 0xe000
	s_nop 0
	global_load_lds_dwordx4 v204, s[66:67]
	s_waitcnt vmcnt(8)
	s_waitcnt lgkmcnt(0)
	s_barrier
	s_setprio 0
	s_waitcnt lgkmcnt(0)
	v_mfma_f32_16x16x32_bf16 v[124:127], v[128:131], v[160:163], v[124:127]
	v_mfma_f32_16x16x32_bf16 v[120:123], v[136:139], v[160:163], v[120:123]
	v_mfma_f32_16x16x32_bf16 v[112:115], v[128:131], v[168:171], v[112:115]
	v_mfma_f32_16x16x32_bf16 v[104:107], v[136:139], v[168:171], v[104:107]
	v_mfma_f32_16x16x32_bf16 v[96:99], v[128:131], v[176:179], v[96:99]
	v_mfma_f32_16x16x32_bf16 v[88:91], v[136:139], v[176:179], v[88:91]
	v_mfma_f32_16x16x32_bf16 v[80:83], v[128:131], v[184:187], v[80:83]
	v_mfma_f32_16x16x32_bf16 v[72:75], v[136:139], v[184:187], v[72:75]
	v_mfma_f32_16x16x32_bf16 v[124:127], v[132:135], v[164:167], v[124:127]
	v_mfma_f32_16x16x32_bf16 v[120:123], v[140:143], v[164:167], v[120:123]
	v_mfma_f32_16x16x32_bf16 v[112:115], v[132:135], v[172:175], v[112:115]
	v_mfma_f32_16x16x32_bf16 v[104:107], v[140:143], v[172:175], v[104:107]
	v_mfma_f32_16x16x32_bf16 v[96:99], v[132:135], v[180:183], v[96:99]
	v_mfma_f32_16x16x32_bf16 v[88:91], v[140:143], v[180:183], v[88:91]
	v_mfma_f32_16x16x32_bf16 v[80:83], v[132:135], v[188:191], v[80:83]
	v_mfma_f32_16x16x32_bf16 v[72:75], v[140:143], v[188:191], v[72:75]
	v_mfma_f32_16x16x32_bf16 v[116:119], v[144:147], v[160:163], v[116:119]
	v_mfma_f32_16x16x32_bf16 v[108:111], v[152:155], v[160:163], v[108:111]
	v_mfma_f32_16x16x32_bf16 v[100:103], v[144:147], v[168:171], v[100:103]
	v_mfma_f32_16x16x32_bf16 v[92:95], v[152:155], v[168:171], v[92:95]
	v_mfma_f32_16x16x32_bf16 v[84:87], v[144:147], v[176:179], v[84:87]
	v_mfma_f32_16x16x32_bf16 v[76:79], v[152:155], v[176:179], v[76:79]
	v_mfma_f32_16x16x32_bf16 v[68:71], v[144:147], v[184:187], v[68:71]
	v_mfma_f32_16x16x32_bf16 v[64:67], v[152:155], v[184:187], v[64:67]
	v_mfma_f32_16x16x32_bf16 v[116:119], v[148:151], v[164:167], v[116:119]
	v_mfma_f32_16x16x32_bf16 v[108:111], v[156:159], v[164:167], v[108:111]
	v_mfma_f32_16x16x32_bf16 v[100:103], v[148:151], v[172:175], v[100:103]
	v_mfma_f32_16x16x32_bf16 v[92:95], v[156:159], v[172:175], v[92:95]
	v_mfma_f32_16x16x32_bf16 v[84:87], v[148:151], v[180:183], v[84:87]
	v_mfma_f32_16x16x32_bf16 v[76:79], v[156:159], v[180:183], v[76:79]
	v_mfma_f32_16x16x32_bf16 v[68:71], v[148:151], v[188:191], v[68:71]
	v_mfma_f32_16x16x32_bf16 v[64:67], v[156:159], v[188:191], v[64:67]
	s_barrier
	s_setprio 1
	s_add_i32 s3, s3, s49
	s_mov_b32 m0, s3
	ds_read_b128 v[160:163], v223 offset:16384
	ds_read_b128 v[164:167], v223 offset:17408
	ds_read_b128 v[168:171], v223 offset:18432
	ds_read_b128 v[172:175], v223 offset:19456
	ds_read_b128 v[176:179], v223 offset:20480
	ds_read_b128 v[180:183], v223 offset:21504
	ds_read_b128 v[184:187], v223 offset:22528
	ds_read_b128 v[188:191], v223 offset:23552
	global_load_lds_dwordx4 v192, s[96:97]
	s_add_i32 m0, s3, 0x2000
	s_add_u32 s66, s96, s34
	s_addc_u32 s67, s97, 0
	s_add_i32 s3, s30, s49
	global_load_lds_dwordx4 v198, s[96:97]
	v_lshl_add_u64 v[212:213], s[66:67], 0, v[192:193]
	s_mov_b32 m0, s3
	v_lshl_add_u64 v[214:215], s[66:67], 0, v[198:199]
	global_load_lds_dwordx4 v192, s[66:67]
	s_add_i32 m0, s3, 0x2000
	s_nop 0
	global_load_lds_dwordx4 v198, s[66:67]
	s_mov_b32 m0, s62
	s_nop 0
	global_load_lds_dwordx4 v202, s[82:83]
	s_mov_b32 m0, s63
	s_nop 0
	global_load_lds_dwordx4 v200, s[82:83]
	s_waitcnt vmcnt(8)
	s_waitcnt lgkmcnt(0)
	s_barrier
	s_setprio 0
	s_waitcnt lgkmcnt(0)
	v_mfma_f32_16x16x32_bf16 v[60:63], v[128:131], v[160:163], v[60:63]
	v_mfma_f32_16x16x32_bf16 v[56:59], v[136:139], v[160:163], v[56:59]
	v_mfma_f32_16x16x32_bf16 v[48:51], v[128:131], v[168:171], v[48:51]
	v_mfma_f32_16x16x32_bf16 v[40:43], v[136:139], v[168:171], v[40:43]
	v_mfma_f32_16x16x32_bf16 v[32:35], v[128:131], v[176:179], v[32:35]
	v_mfma_f32_16x16x32_bf16 v[24:27], v[136:139], v[176:179], v[24:27]
	v_mfma_f32_16x16x32_bf16 v[16:19], v[128:131], v[184:187], v[16:19]
	v_mfma_f32_16x16x32_bf16 v[8:11], v[136:139], v[184:187], v[8:11]
	v_mfma_f32_16x16x32_bf16 v[60:63], v[132:135], v[164:167], v[60:63]
	v_mfma_f32_16x16x32_bf16 v[56:59], v[140:143], v[164:167], v[56:59]
	v_mfma_f32_16x16x32_bf16 v[48:51], v[132:135], v[172:175], v[48:51]
	v_mfma_f32_16x16x32_bf16 v[40:43], v[140:143], v[172:175], v[40:43]
	v_mfma_f32_16x16x32_bf16 v[32:35], v[132:135], v[180:183], v[32:35]
	v_mfma_f32_16x16x32_bf16 v[24:27], v[140:143], v[180:183], v[24:27]
	v_mfma_f32_16x16x32_bf16 v[16:19], v[132:135], v[188:191], v[16:19]
	v_mfma_f32_16x16x32_bf16 v[8:11], v[140:143], v[188:191], v[8:11]
	v_mfma_f32_16x16x32_bf16 v[52:55], v[144:147], v[160:163], v[52:55]
	v_mfma_f32_16x16x32_bf16 v[44:47], v[152:155], v[160:163], v[44:47]
	v_mfma_f32_16x16x32_bf16 v[36:39], v[144:147], v[168:171], v[36:39]
	v_mfma_f32_16x16x32_bf16 v[28:31], v[152:155], v[168:171], v[28:31]
	v_mfma_f32_16x16x32_bf16 v[20:23], v[144:147], v[176:179], v[20:23]
	v_mfma_f32_16x16x32_bf16 v[12:15], v[152:155], v[176:179], v[12:15]
	v_mfma_f32_16x16x32_bf16 v[4:7], v[144:147], v[184:187], v[4:7]
	v_mfma_f32_16x16x32_bf16 v[0:3], v[152:155], v[184:187], v[0:3]
	v_mfma_f32_16x16x32_bf16 v[52:55], v[148:151], v[164:167], v[52:55]
	v_mfma_f32_16x16x32_bf16 v[44:47], v[156:159], v[164:167], v[44:47]
	v_mfma_f32_16x16x32_bf16 v[36:39], v[148:151], v[172:175], v[36:39]
	v_mfma_f32_16x16x32_bf16 v[28:31], v[156:159], v[172:175], v[28:31]
	v_mfma_f32_16x16x32_bf16 v[20:23], v[148:151], v[180:183], v[20:23]
	v_mfma_f32_16x16x32_bf16 v[12:15], v[156:159], v[180:183], v[12:15]
	v_mfma_f32_16x16x32_bf16 v[4:7], v[148:151], v[188:191], v[4:7]
	v_mfma_f32_16x16x32_bf16 v[0:3], v[156:159], v[188:191], v[0:3]
	s_barrier
; #define PG8_STAGE(bufoff, gbase, voff) do { _Pragma("unroll") for (int _i = 0; _i < 2; ++_i) \
;         __builtin_amdgcn_global_load_lds((const unsigned*)((const char*)(gbase) + (voff)[_i]), (PG8_LAS unsigned*)(lds + (bufoff) + ldsw + _i * 8192), 16, 0, 0); } while (0)
; #define PG8_LDA(dst, b, h) do { _Pragma("unroll") for (int m = 0; m < 4; ++m) _Pragma("unroll") for (int k = 0; k < 2; ++k) dst[m][k] = *(const PG8_LAS bf16x8*)(lds + PG8_SA(b, h) + aoff + m * 2048 + k * 1024); } while (0)
; #define PG8_LDB(dst, b, h) do { _Pragma("unroll") for (int n = 0; n < 2; ++n) _Pragma("unroll") for (int k = 0; k < 2; ++k) dst[n][k] = *(const PG8_LAS bf16x8*)(lds + PG8_SB(b, h) + boff + n * 2048 + k * 1024); } while (0)
; #define PG8_MMA(ai, bj, At, Bt) do { __builtin_amdgcn_s_setprio(1); _Pragma("unroll") for (int m = 0; m < 4; ++m) _Pragma("unroll") for (int n = 0; n < 2; ++n) _Pragma("unroll") for (int k = 0; k < 2; ++k) \
;         acc[ai][bj][m][n] = __builtin_amdgcn_mfma_f32_16x16x32_bf16(Bt[n][k], At[m][k], acc[ai][bj][m][n], 0, 0, 0); __builtin_amdgcn_s_setprio(0); } while (0)
; #define PG8_WAIT_V(n) asm volatile("s_waitcnt vmcnt(" #n ")" ::: "memory")
; #define PG8_WAIT_L(n) asm volatile("s_waitcnt lgkmcnt(" #n ")" ::: "memory")
; #define PG8_BAR __builtin_amdgcn_s_barrier()
; #define PG8_SCHED __builtin_amdgcn_sched_barrier(0)
; template <class Epi, class Sched, bool ALIGN_EPI = false, bool SP2 = false>
; __device__ __forceinline__ void gemm_phase(PG8_LAS unsigned char* lds, const Gemm g, const Sched& S, const Epi& E) {
;     ...
;             PG8_LDB(B0, 1, 0); PG8_LDB(B1, 1, 1); PG8_SCHED; PG8_LDA(At, 1, 0); PG8_STAGE(PG8_SA(0, 1), a2 + hstepA, voffA);
;             PG8_WAIT_V(8); PG8_WAIT_L(0); PG8_BAR; PG8_MMA(0, 0, At, B0); PG8_MMA(0, 1, At, B1); PG8_BAR; PG8_SCHED;
;             PG8_LDA(At, 1, 1); PG8_STAGE(PG8_SB(1, 0), b3, voffB); PG8_STAGE(PG8_SB(1, 1), b3 + hstepB, voffB); PG8_STAGE(PG8_SA(1, 0), a3, voffA);
;             PG8_WAIT_V(8); PG8_WAIT_L(0); PG8_BAR; PG8_MMA(1, 0, At, B0); PG8_MMA(1, 1, At, B1); PG8_BAR; PG8_SCHED;
	s_setprio 1
	s_add_i32 s3, 0, 0x18000
	s_add_i32 s30, 0, 0x1c000
	v_add_u32_e32 v140, s3, v222
	v_add_u32_e32 v156, s30, v222
	ds_read_b128 v[128:131], v140
	ds_read_b128 v[132:135], v140 offset:1024
	ds_read_b128 v[136:139], v140 offset:2048
	ds_read_b128 v[140:143], v140 offset:3072
	ds_read_b128 v[144:147], v156
	ds_read_b128 v[148:151], v156 offset:1024
	ds_read_b128 v[152:155], v156 offset:2048
	ds_read_b128 v[156:159], v156 offset:3072
	s_add_u32 s66, s82, 0x130000
	s_addc_u32 s67, s83, 0
	s_mov_b32 m0, s64
	ds_read_b128 v[160:163], v223 offset:32768
	ds_read_b128 v[164:167], v223 offset:33792
	ds_read_b128 v[168:171], v223 offset:34816
	ds_read_b128 v[172:175], v223 offset:35840
	ds_read_b128 v[176:179], v223 offset:36864
	ds_read_b128 v[180:183], v223 offset:37888
	ds_read_b128 v[184:187], v223 offset:38912
	ds_read_b128 v[188:191], v223 offset:39936
	global_load_lds_dwordx4 v202, s[66:67]
	s_mov_b32 m0, s65
	s_nop 0
	global_load_lds_dwordx4 v200, s[66:67]
	s_waitcnt vmcnt(8)
	s_waitcnt lgkmcnt(0)
	s_barrier
	s_setprio 0
	s_waitcnt lgkmcnt(0)
	v_mfma_f32_16x16x32_bf16 v[124:127], v[128:131], v[160:163], v[124:127]
	v_mfma_f32_16x16x32_bf16 v[120:123], v[136:139], v[160:163], v[120:123]
	v_mfma_f32_16x16x32_bf16 v[112:115], v[128:131], v[168:171], v[112:115]
	v_mfma_f32_16x16x32_bf16 v[104:107], v[136:139], v[168:171], v[104:107]
	v_mfma_f32_16x16x32_bf16 v[96:99], v[128:131], v[176:179], v[96:99]
	v_mfma_f32_16x16x32_bf16 v[88:91], v[136:139], v[176:179], v[88:91]
	v_mfma_f32_16x16x32_bf16 v[80:83], v[128:131], v[184:187], v[80:83]
	v_mfma_f32_16x16x32_bf16 v[72:75], v[136:139], v[184:187], v[72:75]
	v_mfma_f32_16x16x32_bf16 v[124:127], v[132:135], v[164:167], v[124:127]
	v_mfma_f32_16x16x32_bf16 v[120:123], v[140:143], v[164:167], v[120:123]
	v_mfma_f32_16x16x32_bf16 v[112:115], v[132:135], v[172:175], v[112:115]
	v_mfma_f32_16x16x32_bf16 v[104:107], v[140:143], v[172:175], v[104:107]
	v_mfma_f32_16x16x32_bf16 v[96:99], v[132:135], v[180:183], v[96:99]
	v_mfma_f32_16x16x32_bf16 v[88:91], v[140:143], v[180:183], v[88:91]
	v_mfma_f32_16x16x32_bf16 v[80:83], v[132:135], v[188:191], v[80:83]
	v_mfma_f32_16x16x32_bf16 v[72:75], v[140:143], v[188:191], v[72:75]
	v_mfma_f32_16x16x32_bf16 v[116:119], v[144:147], v[160:163], v[116:119]
	v_mfma_f32_16x16x32_bf16 v[108:111], v[152:155], v[160:163], v[108:111]
	v_mfma_f32_16x16x32_bf16 v[100:103], v[144:147], v[168:171], v[100:103]
	v_mfma_f32_16x16x32_bf16 v[92:95], v[152:155], v[168:171], v[92:95]
	v_mfma_f32_16x16x32_bf16 v[84:87], v[144:147], v[176:179], v[84:87]
	v_mfma_f32_16x16x32_bf16 v[76:79], v[152:155], v[176:179], v[76:79]
	v_mfma_f32_16x16x32_bf16 v[68:71], v[144:147], v[184:187], v[68:71]
	v_mfma_f32_16x16x32_bf16 v[64:67], v[152:155], v[184:187], v[64:67]
	v_mfma_f32_16x16x32_bf16 v[116:119], v[148:151], v[164:167], v[116:119]
	v_mfma_f32_16x16x32_bf16 v[108:111], v[156:159], v[164:167], v[108:111]
	v_mfma_f32_16x16x32_bf16 v[100:103], v[148:151], v[172:175], v[100:103]
	v_mfma_f32_16x16x32_bf16 v[92:95], v[156:159], v[172:175], v[92:95]
	v_mfma_f32_16x16x32_bf16 v[84:87], v[148:151], v[180:183], v[84:87]
	v_mfma_f32_16x16x32_bf16 v[76:79], v[156:159], v[180:183], v[76:79]
	v_mfma_f32_16x16x32_bf16 v[68:71], v[148:151], v[188:191], v[68:71]
	v_mfma_f32_16x16x32_bf16 v[64:67], v[156:159], v[188:191], v[64:67]
	s_barrier
	s_setprio 1
	s_add_i32 s3, s3, s49
	s_add_i32 m0, s3, 0xffffff80
	ds_read_b128 v[160:163], v223 offset:49152
	ds_read_b128 v[164:167], v223 offset:50176
	ds_read_b128 v[168:171], v223 offset:51200
	ds_read_b128 v[172:175], v223 offset:52224
	ds_read_b128 v[176:179], v223 offset:53248
	ds_read_b128 v[180:183], v223 offset:54272
	ds_read_b128 v[184:187], v223 offset:55296
	ds_read_b128 v[188:191], v223 offset:56320
	global_load_lds_dwordx4 v192, s[96:97] offset:128
	s_add_i32 m0, s3, 0x1f80
	s_add_i32 s3, s30, s49
	global_load_lds_dwordx4 v198, s[96:97] offset:128
	v_lshl_add_u64 v[208:209], v[212:213], 0, s[36:37]
	s_mov_b32 m0, s3
	s_nop 0
	global_load_lds_dwordx4 v[208:209], off
	v_lshl_add_u64 v[208:209], v[214:215], 0, s[36:37]
	s_add_i32 m0, s3, 0x2000
	s_nop 0
	global_load_lds_dwordx4 v[208:209], off
	s_add_i32 m0, s86, 0xffffff80
	s_nop 0
	global_load_lds_dwordx4 v202, s[82:83] offset:128
	s_add_i32 m0, s87, 0xffffff80
	s_nop 0
	global_load_lds_dwordx4 v200, s[82:83] offset:128
	s_waitcnt vmcnt(8)
	s_waitcnt lgkmcnt(0)
	s_barrier
	s_setprio 0
	s_waitcnt lgkmcnt(0)
	v_mfma_f32_16x16x32_bf16 v[60:63], v[128:131], v[160:163], v[60:63]
	v_mfma_f32_16x16x32_bf16 v[56:59], v[136:139], v[160:163], v[56:59]
	v_mfma_f32_16x16x32_bf16 v[48:51], v[128:131], v[168:171], v[48:51]
	v_mfma_f32_16x16x32_bf16 v[40:43], v[136:139], v[168:171], v[40:43]
	v_mfma_f32_16x16x32_bf16 v[32:35], v[128:131], v[176:179], v[32:35]
	v_mfma_f32_16x16x32_bf16 v[24:27], v[136:139], v[176:179], v[24:27]
	v_mfma_f32_16x16x32_bf16 v[16:19], v[128:131], v[184:187], v[16:19]
	v_mfma_f32_16x16x32_bf16 v[8:11], v[136:139], v[184:187], v[8:11]
	v_mfma_f32_16x16x32_bf16 v[60:63], v[132:135], v[164:167], v[60:63]
	v_mfma_f32_16x16x32_bf16 v[56:59], v[140:143], v[164:167], v[56:59]
	v_mfma_f32_16x16x32_bf16 v[48:51], v[132:135], v[172:175], v[48:51]
	v_mfma_f32_16x16x32_bf16 v[40:43], v[140:143], v[172:175], v[40:43]
	v_mfma_f32_16x16x32_bf16 v[32:35], v[132:135], v[180:183], v[32:35]
	v_mfma_f32_16x16x32_bf16 v[24:27], v[140:143], v[180:183], v[24:27]
	v_mfma_f32_16x16x32_bf16 v[16:19], v[132:135], v[188:191], v[16:19]
	v_mfma_f32_16x16x32_bf16 v[8:11], v[140:143], v[188:191], v[8:11]
	v_mfma_f32_16x16x32_bf16 v[52:55], v[144:147], v[160:163], v[52:55]
	v_mfma_f32_16x16x32_bf16 v[44:47], v[152:155], v[160:163], v[44:47]
	v_mfma_f32_16x16x32_bf16 v[36:39], v[144:147], v[168:171], v[36:39]
	v_mfma_f32_16x16x32_bf16 v[28:31], v[152:155], v[168:171], v[28:31]
	v_mfma_f32_16x16x32_bf16 v[20:23], v[144:147], v[176:179], v[20:23]
	v_mfma_f32_16x16x32_bf16 v[12:15], v[152:155], v[176:179], v[12:15]
	v_mfma_f32_16x16x32_bf16 v[4:7], v[144:147], v[184:187], v[4:7]
	v_mfma_f32_16x16x32_bf16 v[0:3], v[152:155], v[184:187], v[0:3]
	v_mfma_f32_16x16x32_bf16 v[52:55], v[148:151], v[164:167], v[52:55]
	v_mfma_f32_16x16x32_bf16 v[44:47], v[156:159], v[164:167], v[44:47]
	v_mfma_f32_16x16x32_bf16 v[36:39], v[148:151], v[172:175], v[36:39]
	v_mfma_f32_16x16x32_bf16 v[28:31], v[156:159], v[172:175], v[28:31]
	v_mfma_f32_16x16x32_bf16 v[20:23], v[148:151], v[180:183], v[20:23]
	v_mfma_f32_16x16x32_bf16 v[12:15], v[156:159], v[180:183], v[12:15]
	v_mfma_f32_16x16x32_bf16 v[4:7], v[148:151], v[188:191], v[4:7]
	v_mfma_f32_16x16x32_bf16 v[0:3], v[156:159], v[188:191], v[0:3]
	s_barrier
	s_setprio 1
	s_add_u32 s93, s93, 0x100
	s_addc_u32 s94, s94, 0
	s_cmp_ge_u32 s2, s80
	s_mov_b64 s[66:67], s[4:5]
	s_mov_b32 s82, s2
	s_cbranch_scc0 .LBB0_766
	s_and_b64 vcc, exec, s[12:13]
	s_cbranch_vccz .LBB0_769
	s_barrier

; #define PG8_STAGE(bufoff, gbase, voff) do { _Pragma("unroll") for (int _i = 0; _i < 2; ++_i) \
;         __builtin_amdgcn_global_load_lds((const unsigned*)((const char*)(gbase) + (voff)[_i]), (PG8_LAS unsigned*)(lds + (bufoff) + ldsw + _i * 8192), 16, 0, 0); } while (0)
; #define PG8_LDA(dst, b, h) do { _Pragma("unroll") for (int m = 0; m < 4; ++m) _Pragma("unroll") for (int k = 0; k < 2; ++k) dst[m][k] = *(const PG8_LAS bf16x8*)(lds + PG8_SA(b, h) + aoff + m * 2048 + k * 1024); } while (0)
; #define PG8_LDB(dst, b, h) do { _Pragma("unroll") for (int n = 0; n < 2; ++n) _Pragma("unroll") for (int k = 0; k < 2; ++k) dst[n][k] = *(const PG8_LAS bf16x8*)(lds + PG8_SB(b, h) + boff + n * 2048 + k * 1024); } while (0)
; #define PG8_MMA(ai, bj, At, Bt) do { __builtin_amdgcn_s_setprio(1); _Pragma("unroll") for (int m = 0; m < 4; ++m) _Pragma("unroll") for (int n = 0; n < 2; ++n) _Pragma("unroll") for (int k = 0; k < 2; ++k) \
;         acc[ai][bj][m][n] = __builtin_amdgcn_mfma_f32_16x16x32_bf16(Bt[n][k], At[m][k], acc[ai][bj][m][n], 0, 0, 0); __builtin_amdgcn_s_setprio(0); } while (0)
; #define PG8_WAIT_V(n) asm volatile("s_waitcnt vmcnt(" #n ")" ::: "memory")
; #define PG8_WAIT_L(n) asm volatile("s_waitcnt lgkmcnt(" #n ")" ::: "memory")
; #define PG8_BAR __builtin_amdgcn_s_barrier()
; template <class Epi, class Sched, bool ALIGN_EPI = false, bool SP2 = false>
; __device__ __forceinline__ void gemm_phase(PG8_LAS unsigned char* lds, const Gemm g, const Sched& S, const Epi& E) {
;     ...
;             const char* a1 = cA + (size_t)(t + 1) * kstep;
;             const char* a2 = last ? nA : cA + (size_t)(t + 2) * kstep; const char* b2 = last ? nB : cB + (size_t)(t + 2) * kstep;
;             const char* a3 = a2 + kstep; const char* b3 = b2 + kstep;
;             if (last && has_next) S.a_ready(nxt);
;             if constexpr (SP2) {
;             PG8_LDB(B0, 0, 0); PG8_LDB(B1, 0, 1); PG8_SCHED; PG8_LDA(At, 0, 0); PG8_STAGE(PG8_SA(1, 1), a1 + hstepA, voffA);
;             PG8_WAIT_V(8); PG8_WAIT_L(0); PG8_BAR; PG8_MMA(0, 0, At, B0); PG8_MMA(0, 1, At, B1); PG8_BAR; PG8_SCHED;
;             PG8_LDA(At, 0, 1); PG8_STAGE(PG8_SB(0, 0), b2, voffB); PG8_STAGE(PG8_SB(0, 1), b2 + hstepB, voffB); PG8_STAGE(PG8_SA(0, 0), a2, voffA);
;             PG8_WAIT_V(8); PG8_WAIT_L(0); PG8_BAR; PG8_MMA(1, 0, At, B0); PG8_MMA(1, 1, At, B1); PG8_BAR; PG8_SCHED;
.LBB0_817:
	s_add_u32 s2, s0, 0xfffc0080
	s_addc_u32 s3, s1, -1
	s_add_i32 s30, 0, 0x10000
	s_cmp_eq_u32 s78, 12
	s_cselect_b32 s11, s7, s3
	s_cselect_b32 s10, s12, s2
	s_cselect_b32 s9, s13, s17
	s_cselect_b32 s8, s15, s16
	s_add_i32 s31, 0, 0x14000
	v_add_u32_e32 v84, s30, v240
	v_add_u32_e32 v116, s31, v240
	ds_read_b128 v[72:75], v84
	ds_read_b128 v[76:79], v84 offset:1024
	ds_read_b128 v[80:83], v84 offset:2048
	ds_read_b128 v[84:87], v84 offset:3072
	ds_read_b128 v[104:107], v116
	ds_read_b128 v[108:111], v116 offset:1024
	ds_read_b128 v[112:115], v116 offset:2048
	ds_read_b128 v[116:119], v116 offset:3072
	s_add_i32 m0, s19, 0xc000
	ds_read_b128 v[136:139], v241
	ds_read_b128 v[140:143], v241 offset:1024
	ds_read_b128 v[144:147], v241 offset:2048
	ds_read_b128 v[148:151], v241 offset:3072
	ds_read_b128 v[168:171], v241 offset:4096
	ds_read_b128 v[172:175], v241 offset:5120
	ds_read_b128 v[176:179], v241 offset:6144
	ds_read_b128 v[180:183], v241 offset:7168
	global_load_lds_dwordx4 v206, s[0:1]
	s_add_i32 m0, s19, 0xe000
	s_nop 0
	global_load_lds_dwordx4 v204, s[0:1]
	s_waitcnt vmcnt(8)
	s_waitcnt lgkmcnt(0)
	s_barrier
	s_setprio 0
	s_waitcnt lgkmcnt(0)
	v_mfma_f32_16x16x32_bf16 v[188:191], v[72:75], v[136:139], v[188:191]
	v_mfma_f32_16x16x32_bf16 v[184:187], v[80:83], v[136:139], v[184:187]
	v_mfma_f32_16x16x32_bf16 v[156:159], v[72:75], v[144:147], v[156:159]
	v_mfma_f32_16x16x32_bf16 v[152:155], v[80:83], v[144:147], v[152:155]
	v_mfma_f32_16x16x32_bf16 v[124:127], v[72:75], v[168:171], v[124:127]
	v_mfma_f32_16x16x32_bf16 v[120:123], v[80:83], v[168:171], v[120:123]
	v_mfma_f32_16x16x32_bf16 v[92:95], v[72:75], v[176:179], v[92:95]
	v_mfma_f32_16x16x32_bf16 v[88:91], v[80:83], v[176:179], v[88:91]
	v_mfma_f32_16x16x32_bf16 v[188:191], v[76:79], v[140:143], v[188:191]
	v_mfma_f32_16x16x32_bf16 v[184:187], v[84:87], v[140:143], v[184:187]
	v_mfma_f32_16x16x32_bf16 v[156:159], v[76:79], v[148:151], v[156:159]
	v_mfma_f32_16x16x32_bf16 v[152:155], v[84:87], v[148:151], v[152:155]
	v_mfma_f32_16x16x32_bf16 v[124:127], v[76:79], v[172:175], v[124:127]
	v_mfma_f32_16x16x32_bf16 v[120:123], v[84:87], v[172:175], v[120:123]
	v_mfma_f32_16x16x32_bf16 v[92:95], v[76:79], v[180:183], v[92:95]
	v_mfma_f32_16x16x32_bf16 v[88:91], v[84:87], v[180:183], v[88:91]
	v_mfma_f32_16x16x32_bf16 v[164:167], v[104:107], v[136:139], v[164:167]
	v_mfma_f32_16x16x32_bf16 v[132:135], v[104:107], v[144:147], v[132:135]
	v_mfma_f32_16x16x32_bf16 v[128:131], v[112:115], v[144:147], v[128:131]
	v_mfma_f32_16x16x32_bf16 v[100:103], v[104:107], v[168:171], v[100:103]
	v_mfma_f32_16x16x32_bf16 v[96:99], v[112:115], v[168:171], v[96:99]
	v_mfma_f32_16x16x32_bf16 v[68:71], v[104:107], v[176:179], v[68:71]
	v_mfma_f32_16x16x32_bf16 v[64:67], v[112:115], v[176:179], v[64:67]
	v_mfma_f32_16x16x32_bf16 v[164:167], v[108:111], v[140:143], v[164:167]
	v_mfma_f32_16x16x32_bf16 v[136:139], v[112:115], v[136:139], v[160:163]
	v_mfma_f32_16x16x32_bf16 v[132:135], v[108:111], v[148:151], v[132:135]
	v_mfma_f32_16x16x32_bf16 v[128:131], v[116:119], v[148:151], v[128:131]
	v_mfma_f32_16x16x32_bf16 v[100:103], v[108:111], v[172:175], v[100:103]
	v_mfma_f32_16x16x32_bf16 v[96:99], v[116:119], v[172:175], v[96:99]
	v_mfma_f32_16x16x32_bf16 v[68:71], v[108:111], v[180:183], v[68:71]
	v_mfma_f32_16x16x32_bf16 v[64:67], v[116:119], v[180:183], v[64:67]
	v_mfma_f32_16x16x32_bf16 v[136:139], v[116:119], v[140:143], v[136:139]
	s_barrier
	s_setprio 1
	s_add_i32 s2, s30, s18
	s_mov_b32 m0, s2
	ds_read_b128 v[140:143], v241 offset:16384
	ds_read_b128 v[144:147], v241 offset:17408
	ds_read_b128 v[148:151], v241 offset:18432
	ds_read_b128 v[160:163], v241 offset:19456
	ds_read_b128 v[168:171], v241 offset:20480
	ds_read_b128 v[172:175], v241 offset:21504
	ds_read_b128 v[176:179], v241 offset:22528
	ds_read_b128 v[180:183], v241 offset:23552
	global_load_lds_dwordx4 v192, s[8:9]
	s_add_i32 m0, s2, 0x2000
	s_add_u32 s2, s8, 0x40000
	s_addc_u32 s3, s9, 0
	s_add_i32 s30, s31, s18
	global_load_lds_dwordx4 v202, s[8:9]
	s_mov_b32 m0, s30
	s_nop 0
	global_load_lds_dwordx4 v192, s[2:3]
	s_add_i32 m0, s30, 0x2000
	s_nop 0
	global_load_lds_dwordx4 v202, s[2:3]
	s_mov_b32 m0, s19
	s_nop 0
	global_load_lds_dwordx4 v198, s[10:11]
	s_mov_b32 m0, s45
	s_nop 0
	global_load_lds_dwordx4 v200, s[10:11]
	s_waitcnt vmcnt(8)
	s_waitcnt lgkmcnt(0)
	s_barrier
	s_setprio 0
	s_waitcnt lgkmcnt(0)
	v_mfma_f32_16x16x32_bf16 v[60:63], v[72:75], v[140:143], v[60:63]
	v_mfma_f32_16x16x32_bf16 v[56:59], v[80:83], v[140:143], v[56:59]
	v_mfma_f32_16x16x32_bf16 v[44:47], v[72:75], v[148:151], v[44:47]
	v_mfma_f32_16x16x32_bf16 v[40:43], v[80:83], v[148:151], v[40:43]
	v_mfma_f32_16x16x32_bf16 v[28:31], v[72:75], v[168:171], v[28:31]
	v_mfma_f32_16x16x32_bf16 v[24:27], v[80:83], v[168:171], v[24:27]
	v_mfma_f32_16x16x32_bf16 v[12:15], v[72:75], v[176:179], v[12:15]
	v_mfma_f32_16x16x32_bf16 v[8:11], v[80:83], v[176:179], v[8:11]
	v_mfma_f32_16x16x32_bf16 v[60:63], v[76:79], v[144:147], v[60:63]
	v_mfma_f32_16x16x32_bf16 v[56:59], v[84:87], v[144:147], v[56:59]
	v_mfma_f32_16x16x32_bf16 v[44:47], v[76:79], v[160:163], v[44:47]
	v_mfma_f32_16x16x32_bf16 v[40:43], v[84:87], v[160:163], v[40:43]
	v_mfma_f32_16x16x32_bf16 v[28:31], v[76:79], v[172:175], v[28:31]
	v_mfma_f32_16x16x32_bf16 v[24:27], v[84:87], v[172:175], v[24:27]
	v_mfma_f32_16x16x32_bf16 v[12:15], v[76:79], v[180:183], v[12:15]
	v_mfma_f32_16x16x32_bf16 v[8:11], v[84:87], v[180:183], v[8:11]
	v_mfma_f32_16x16x32_bf16 v[52:55], v[104:107], v[140:143], v[52:55]
	v_mfma_f32_16x16x32_bf16 v[48:51], v[112:115], v[140:143], v[48:51]
	v_mfma_f32_16x16x32_bf16 v[36:39], v[104:107], v[148:151], v[36:39]
	v_mfma_f32_16x16x32_bf16 v[32:35], v[112:115], v[148:151], v[32:35]
	v_mfma_f32_16x16x32_bf16 v[20:23], v[104:107], v[168:171], v[20:23]
	v_mfma_f32_16x16x32_bf16 v[16:19], v[112:115], v[168:171], v[16:19]
	v_mfma_f32_16x16x32_bf16 v[4:7], v[104:107], v[176:179], v[4:7]
	v_mfma_f32_16x16x32_bf16 v[0:3], v[112:115], v[176:179], v[0:3]
	v_mfma_f32_16x16x32_bf16 v[52:55], v[108:111], v[144:147], v[52:55]
	v_mfma_f32_16x16x32_bf16 v[48:51], v[116:119], v[144:147], v[48:51]
	v_mfma_f32_16x16x32_bf16 v[36:39], v[108:111], v[160:163], v[36:39]
	v_mfma_f32_16x16x32_bf16 v[32:35], v[116:119], v[160:163], v[32:35]
	v_mfma_f32_16x16x32_bf16 v[20:23], v[108:111], v[172:175], v[20:23]
	v_mfma_f32_16x16x32_bf16 v[16:19], v[116:119], v[172:175], v[16:19]
	v_mfma_f32_16x16x32_bf16 v[4:7], v[108:111], v[180:183], v[4:7]
	v_mfma_f32_16x16x32_bf16 v[0:3], v[116:119], v[180:183], v[0:3]
	s_barrier
; #define PG8_STAGE(bufoff, gbase, voff) do { _Pragma("unroll") for (int _i = 0; _i < 2; ++_i) \
;         __builtin_amdgcn_global_load_lds((const unsigned*)((const char*)(gbase) + (voff)[_i]), (PG8_LAS unsigned*)(lds + (bufoff) + ldsw + _i * 8192), 16, 0, 0); } while (0)
; #define PG8_LDA(dst, b, h) do { _Pragma("unroll") for (int m = 0; m < 4; ++m) _Pragma("unroll") for (int k = 0; k < 2; ++k) dst[m][k] = *(const PG8_LAS bf16x8*)(lds + PG8_SA(b, h) + aoff + m * 2048 + k * 1024); } while (0)
; #define PG8_LDB(dst, b, h) do { _Pragma("unroll") for (int n = 0; n < 2; ++n) _Pragma("unroll") for (int k = 0; k < 2; ++k) dst[n][k] = *(const PG8_LAS bf16x8*)(lds + PG8_SB(b, h) + boff + n * 2048 + k * 1024); } while (0)
; #define PG8_MMA(ai, bj, At, Bt) do { __builtin_amdgcn_s_setprio(1); _Pragma("unroll") for (int m = 0; m < 4; ++m) _Pragma("unroll") for (int n = 0; n < 2; ++n) _Pragma("unroll") for (int k = 0; k < 2; ++k) \
;         acc[ai][bj][m][n] = __builtin_amdgcn_mfma_f32_16x16x32_bf16(Bt[n][k], At[m][k], acc[ai][bj][m][n], 0, 0, 0); __builtin_amdgcn_s_setprio(0); } while (0)
; #define PG8_WAIT_V(n) asm volatile("s_waitcnt vmcnt(" #n ")" ::: "memory")
; #define PG8_WAIT_L(n) asm volatile("s_waitcnt lgkmcnt(" #n ")" ::: "memory")
; #define PG8_BAR __builtin_amdgcn_s_barrier()
; #define PG8_SCHED __builtin_amdgcn_sched_barrier(0)
; template <class Epi, class Sched, bool ALIGN_EPI = false, bool SP2 = false>
; __device__ __forceinline__ void gemm_phase(PG8_LAS unsigned char* lds, const Gemm g, const Sched& S, const Epi& E) {
;     ...
;             PG8_LDB(B0, 1, 0); PG8_LDB(B1, 1, 1); PG8_SCHED; PG8_LDA(At, 1, 0); PG8_STAGE(PG8_SA(0, 1), a2 + hstepA, voffA);
;             PG8_WAIT_V(8); PG8_WAIT_L(0); PG8_BAR; PG8_MMA(0, 0, At, B0); PG8_MMA(0, 1, At, B1); PG8_BAR; PG8_SCHED;
;             PG8_LDA(At, 1, 1); PG8_STAGE(PG8_SB(1, 0), b3, voffB); PG8_STAGE(PG8_SB(1, 1), b3 + hstepB, voffB); PG8_STAGE(PG8_SA(1, 0), a3, voffA);
;             PG8_WAIT_V(8); PG8_WAIT_L(0); PG8_BAR; PG8_MMA(1, 0, At, B0); PG8_MMA(1, 1, At, B1); PG8_BAR; PG8_SCHED;
	s_setprio 1
	s_add_i32 s30, 0, 0x18000
	s_add_i32 s31, 0, 0x1c000
	v_add_u32_e32 v84, s30, v240
	v_add_u32_e32 v116, s31, v240
	ds_read_b128 v[72:75], v84
	ds_read_b128 v[76:79], v84 offset:1024
	ds_read_b128 v[80:83], v84 offset:2048
	ds_read_b128 v[84:87], v84 offset:3072
	ds_read_b128 v[104:107], v116
	ds_read_b128 v[108:111], v116 offset:1024
	ds_read_b128 v[112:115], v116 offset:2048
	ds_read_b128 v[116:119], v116 offset:3072
	s_add_u32 s2, s10, 0x40000
	s_addc_u32 s3, s11, 0
	s_mov_b32 m0, s64
	ds_read_b128 v[140:143], v241 offset:32768
	ds_read_b128 v[144:147], v241 offset:33792
	ds_read_b128 v[148:151], v241 offset:34816
	ds_read_b128 v[168:171], v241 offset:35840
	ds_read_b128 v[172:175], v241 offset:36864
	ds_read_b128 v[176:179], v241 offset:37888
	ds_read_b128 v[180:183], v241 offset:38912
	ds_read_b128 v[208:211], v241 offset:39936
	global_load_lds_dwordx4 v198, s[2:3]
	s_mov_b32 m0, s65
	s_nop 0
	global_load_lds_dwordx4 v200, s[2:3]
	s_waitcnt vmcnt(8)
	s_waitcnt lgkmcnt(0)
	s_barrier
	s_setprio 0
	s_waitcnt lgkmcnt(0)
	v_mfma_f32_16x16x32_bf16 v[160:163], v[72:75], v[140:143], v[188:191]
	v_mfma_f32_16x16x32_bf16 v[188:191], v[76:79], v[144:147], v[160:163]
	v_mfma_f32_16x16x32_bf16 v[160:163], v[80:83], v[140:143], v[184:187]
	v_mfma_f32_16x16x32_bf16 v[156:159], v[72:75], v[148:151], v[156:159]
	v_mfma_f32_16x16x32_bf16 v[152:155], v[80:83], v[148:151], v[152:155]
	v_mfma_f32_16x16x32_bf16 v[124:127], v[72:75], v[172:175], v[124:127]
	v_mfma_f32_16x16x32_bf16 v[120:123], v[80:83], v[172:175], v[120:123]
	v_mfma_f32_16x16x32_bf16 v[92:95], v[72:75], v[180:183], v[92:95]
	v_mfma_f32_16x16x32_bf16 v[88:91], v[80:83], v[180:183], v[88:91]
	v_mfma_f32_16x16x32_bf16 v[184:187], v[84:87], v[144:147], v[160:163]
	v_mfma_f32_16x16x32_bf16 v[156:159], v[76:79], v[168:171], v[156:159]
	v_mfma_f32_16x16x32_bf16 v[152:155], v[84:87], v[168:171], v[152:155]
	v_mfma_f32_16x16x32_bf16 v[124:127], v[76:79], v[176:179], v[124:127]
	v_mfma_f32_16x16x32_bf16 v[120:123], v[84:87], v[176:179], v[120:123]
	v_mfma_f32_16x16x32_bf16 v[92:95], v[76:79], v[208:211], v[92:95]
	v_mfma_f32_16x16x32_bf16 v[88:91], v[84:87], v[208:211], v[88:91]
	v_mfma_f32_16x16x32_bf16 v[160:163], v[104:107], v[140:143], v[164:167]
	v_mfma_f32_16x16x32_bf16 v[136:139], v[112:115], v[140:143], v[136:139]
	v_mfma_f32_16x16x32_bf16 v[132:135], v[104:107], v[148:151], v[132:135]
	v_mfma_f32_16x16x32_bf16 v[128:131], v[112:115], v[148:151], v[128:131]
	v_mfma_f32_16x16x32_bf16 v[100:103], v[104:107], v[172:175], v[100:103]
	v_mfma_f32_16x16x32_bf16 v[96:99], v[112:115], v[172:175], v[96:99]
	v_mfma_f32_16x16x32_bf16 v[68:71], v[104:107], v[180:183], v[68:71]
	v_mfma_f32_16x16x32_bf16 v[64:67], v[112:115], v[180:183], v[64:67]
	v_mfma_f32_16x16x32_bf16 v[164:167], v[108:111], v[144:147], v[160:163]
	v_mfma_f32_16x16x32_bf16 v[160:163], v[116:119], v[144:147], v[136:139]
	v_mfma_f32_16x16x32_bf16 v[132:135], v[108:111], v[168:171], v[132:135]
	v_mfma_f32_16x16x32_bf16 v[128:131], v[116:119], v[168:171], v[128:131]
	v_mfma_f32_16x16x32_bf16 v[100:103], v[108:111], v[176:179], v[100:103]
	v_mfma_f32_16x16x32_bf16 v[96:99], v[116:119], v[176:179], v[96:99]
	v_mfma_f32_16x16x32_bf16 v[68:71], v[108:111], v[208:211], v[68:71]
	v_mfma_f32_16x16x32_bf16 v[64:67], v[116:119], v[208:211], v[64:67]
	s_barrier
	s_setprio 1
	s_add_i32 s2, s30, s18
	s_add_i32 m0, s2, 0xffffff80
	ds_read_b128 v[136:139], v241 offset:49152
	ds_read_b128 v[140:143], v241 offset:50176
	ds_read_b128 v[144:147], v241 offset:51200
	ds_read_b128 v[148:151], v241 offset:52224
	ds_read_b128 v[168:171], v241 offset:53248
	ds_read_b128 v[172:175], v241 offset:54272
	ds_read_b128 v[176:179], v241 offset:55296
	ds_read_b128 v[180:183], v241 offset:56320
	global_load_lds_dwordx4 v192, s[8:9] offset:128
	s_add_i32 m0, s2, 0x1f80
	s_add_u32 s2, s8, 0x40080
	global_load_lds_dwordx4 v202, s[8:9] offset:128
	s_addc_u32 s3, s9, 0
	s_add_i32 s8, s31, s18
	s_mov_b32 m0, s8
	s_nop 0
	global_load_lds_dwordx4 v192, s[2:3]
	s_add_i32 m0, s8, 0x2000
	s_nop 0
	global_load_lds_dwordx4 v202, s[2:3]
	s_add_i32 m0, s21, 0xffffff80
	s_nop 0
	global_load_lds_dwordx4 v198, s[10:11] offset:128
	s_add_i32 m0, s62, 0xffffff80
	s_nop 0
	global_load_lds_dwordx4 v200, s[10:11] offset:128
	s_waitcnt vmcnt(8)
	s_waitcnt lgkmcnt(0)
	s_barrier
	s_setprio 0
	s_waitcnt lgkmcnt(0)
	v_mfma_f32_16x16x32_bf16 v[60:63], v[72:75], v[136:139], v[60:63]
	v_mfma_f32_16x16x32_bf16 v[56:59], v[80:83], v[136:139], v[56:59]
	v_mfma_f32_16x16x32_bf16 v[44:47], v[72:75], v[144:147], v[44:47]
	v_mfma_f32_16x16x32_bf16 v[40:43], v[80:83], v[144:147], v[40:43]
	v_mfma_f32_16x16x32_bf16 v[28:31], v[72:75], v[168:171], v[28:31]
	v_mfma_f32_16x16x32_bf16 v[24:27], v[80:83], v[168:171], v[24:27]
	v_mfma_f32_16x16x32_bf16 v[12:15], v[72:75], v[176:179], v[12:15]
	v_mfma_f32_16x16x32_bf16 v[8:11], v[80:83], v[176:179], v[8:11]
	v_mfma_f32_16x16x32_bf16 v[60:63], v[76:79], v[140:143], v[60:63]
	v_mfma_f32_16x16x32_bf16 v[56:59], v[84:87], v[140:143], v[56:59]
	v_mfma_f32_16x16x32_bf16 v[44:47], v[76:79], v[148:151], v[44:47]
	v_mfma_f32_16x16x32_bf16 v[40:43], v[84:87], v[148:151], v[40:43]
	v_mfma_f32_16x16x32_bf16 v[28:31], v[76:79], v[172:175], v[28:31]
	v_mfma_f32_16x16x32_bf16 v[24:27], v[84:87], v[172:175], v[24:27]
	v_mfma_f32_16x16x32_bf16 v[12:15], v[76:79], v[180:183], v[12:15]
	v_mfma_f32_16x16x32_bf16 v[8:11], v[84:87], v[180:183], v[8:11]
	v_mfma_f32_16x16x32_bf16 v[52:55], v[104:107], v[136:139], v[52:55]
	v_mfma_f32_16x16x32_bf16 v[48:51], v[112:115], v[136:139], v[48:51]
	v_mfma_f32_16x16x32_bf16 v[36:39], v[104:107], v[144:147], v[36:39]
	v_mfma_f32_16x16x32_bf16 v[32:35], v[112:115], v[144:147], v[32:35]
	v_mfma_f32_16x16x32_bf16 v[20:23], v[104:107], v[168:171], v[20:23]
	v_mfma_f32_16x16x32_bf16 v[16:19], v[112:115], v[168:171], v[16:19]
	v_mfma_f32_16x16x32_bf16 v[4:7], v[104:107], v[176:179], v[4:7]
	v_mfma_f32_16x16x32_bf16 v[0:3], v[112:115], v[176:179], v[0:3]
	v_mfma_f32_16x16x32_bf16 v[52:55], v[108:111], v[140:143], v[52:55]
	v_mfma_f32_16x16x32_bf16 v[48:51], v[116:119], v[140:143], v[48:51]
	v_mfma_f32_16x16x32_bf16 v[36:39], v[108:111], v[148:151], v[36:39]
	v_mfma_f32_16x16x32_bf16 v[32:35], v[116:119], v[148:151], v[32:35]
	v_mfma_f32_16x16x32_bf16 v[20:23], v[108:111], v[172:175], v[20:23]
	v_mfma_f32_16x16x32_bf16 v[16:19], v[116:119], v[172:175], v[16:19]
	v_mfma_f32_16x16x32_bf16 v[4:7], v[108:111], v[180:183], v[4:7]
	v_mfma_f32_16x16x32_bf16 v[0:3], v[116:119], v[180:183], v[0:3]
	s_barrier
	s_setprio 1
	s_add_i32 s78, s78, 2
	s_add_u32 s16, s16, 0x100
	s_addc_u32 s17, s17, 0
	s_add_u32 s0, s0, 0x100
	s_addc_u32 s1, s1, 0
	s_cmp_gt_u32 s78, 13
	s_cbranch_scc0 .LBB0_817
	s_and_b64 vcc, exec, s[66:67]
	s_cbranch_vccz .LBB0_820
	s_barrier
